# residual-GEMM epilogues: cross-group row sums via v_permlane16/32_swap instead of two ds_bpermute round trips per row block
# baseline (speedup 1.0000x reference)
.LBB0_496:
	s_ashr_i32 s19, s38, 4
	s_mul_hi_i32 s25, s19, 0x6000
	s_mulk_i32 s19, 0x6000
	v_lshl_add_u32 v156, s38, 8, v1
	v_lshl_or_b32 v154, s8, 8, v169
	s_add_u32 s40, s68, s19
	v_ashrrev_i32_e32 v157, 31, v156
	s_addc_u32 s41, s69, s25
	v_ashrrev_i32_e32 v155, 31, v154
	v_lshlrev_b64 v[74:75], 10, v[156:157]
	v_lshl_add_u64 v[200:201], v[74:75], 0, v[154:155]
	s_add_u32 s38, s70, s19
	v_lshlrev_b64 v[166:167], 2, v[154:155]
	v_lshl_add_u64 v[206:207], v[200:201], 2, s[36:37]
	s_addc_u32 s39, s71, s25
	v_lshl_add_u64 v[198:199], s[40:41], 0, v[166:167]
	global_load_dwordx4 v[158:161], v[206:207], off
	global_load_dwordx4 v[78:81], v[198:199], off
	global_load_dwordx4 v[74:77], v[198:199], off offset:16
	global_load_dwordx4 v[162:165], v[206:207], off offset:16
	v_lshl_add_u64 v[202:203], s[38:39], 0, v[166:167]
	global_load_dwordx4 v[174:177], v[202:203], off
	global_load_dwordx4 v[178:181], v[202:203], off offset:16
	v_lshl_add_u64 v[166:167], s[50:51], 0, v[166:167]
	global_load_dwordx4 v[182:185], v[166:167], off
	global_load_dwordx4 v[186:189], v[166:167], off offset:16
	v_pk_add_f32 v[208:209], v[88:89], 0 op_sel_hi:[1,0]
	v_pk_add_f32 v[210:211], v[86:87], 0 op_sel_hi:[1,0]
	v_pk_add_f32 v[212:213], v[84:85], 0 op_sel_hi:[1,0]
	v_pk_add_f32 v[214:215], v[82:83], 0 op_sel_hi:[1,0]
	global_load_dwordx4 v[190:193], v[166:167], off offset:528
	global_load_dwordx4 v[194:197], v[166:167], off offset:512
	v_lshlrev_b64 v[166:167], 1, v[200:201]
	v_lshl_add_u64 v[216:217], s[20:21], 0, v[166:167]
	v_lshl_add_u64 v[218:219], s[22:23], 0, v[166:167]
	global_load_dwordx4 v[82:85], v[198:199], off offset:528
	global_load_dwordx4 v[86:89], v[198:199], off offset:512
	s_nop 0
	global_load_dwordx4 v[198:201], v[202:203], off offset:528
	s_nop 0
	global_load_dwordx4 v[202:205], v[202:203], off offset:512
	s_lshl_b32 s38, s8, 2
	s_ashr_i32 s39, s38, 31
	s_waitcnt vmcnt(0)
	v_pk_fma_f32 v[166:167], v[208:209], v[80:81], v[160:161]
	v_pk_fma_f32 v[208:209], v[210:211], v[78:79], v[158:159]
	v_pk_fma_f32 v[210:211], v[212:213], v[76:77], v[164:165]
	v_pk_fma_f32 v[212:213], v[214:215], v[74:75], v[162:163]
	v_cvt_pk_bf16_f32 v158, v208, v209
	v_cvt_pk_bf16_f32 v159, v166, v167
	v_cvt_pk_bf16_f32 v160, v212, v213
	v_cvt_pk_bf16_f32 v161, v210, v211
	v_pk_add_f32 v[162:163], v[176:177], 1.0 op_sel_hi:[1,0]
	v_pk_add_f32 v[164:165], v[174:175], 1.0 op_sel_hi:[1,0]
	v_pk_add_f32 v[174:175], v[180:181], 1.0 op_sel_hi:[1,0]
	v_pk_add_f32 v[176:177], v[178:179], 1.0 op_sel_hi:[1,0]
	global_store_dwordx4 v[216:217], v[158:161], off
	v_pk_mul_f32 v[164:165], v[182:183], v[164:165]
	v_pk_add_f32 v[198:199], v[198:199], 1.0 op_sel_hi:[1,0]
	v_pk_mul_f32 v[160:161], v[184:185], v[162:163]
	v_pk_mul_f32 v[158:159], v[188:189], v[174:175]
	v_pk_mul_f32 v[162:163], v[186:187], v[176:177]
	v_pk_mul_f32 v[176:177], v[160:161], v[166:167]
	v_pk_mul_f32 v[174:175], v[164:165], v[208:209]
	v_pk_mul_f32 v[178:179], v[158:159], v[210:211]
	v_pk_mul_f32 v[180:181], v[162:163], v[212:213]
	v_cvt_pk_bf16_f32 v174, v174, v175
	v_cvt_pk_bf16_f32 v175, v176, v177
	v_cvt_pk_bf16_f32 v176, v180, v181
	v_cvt_pk_bf16_f32 v177, v178, v179
	global_store_dwordx4 v[218:219], v[174:177], off
	global_load_dwordx4 v[176:179], v[206:207], off offset:512
	s_nop 0
	global_load_dwordx4 v[180:183], v[206:207], off offset:528
	v_pk_add_f32 v[206:207], v[130:131], 0 op_sel_hi:[1,0]
	v_and_b32_e32 v131, 64, v173
	v_xor_b32_e32 v130, 16, v173
	v_add_u32_e32 v131, 64, v131
	v_pk_add_f32 v[188:189], v[132:133], 0 op_sel_hi:[1,0]
	v_xor_b32_e32 v132, 32, v173
	v_cmp_lt_i32_e32 vcc, v130, v131
	v_mul_f32_e32 v209, v209, v209
	v_mul_f32_e32 v167, v167, v167
	v_mul_f32_e32 v213, v213, v213
	v_mul_f32_e32 v211, v211, v211
	v_cndmask_b32_e32 v130, v173, v130, vcc
	v_cmp_lt_i32_e32 vcc, v132, v131
	v_fmac_f32_e32 v209, v208, v208
	v_fmac_f32_e32 v167, v166, v166
	v_fmac_f32_e32 v213, v212, v212
	v_fmac_f32_e32 v211, v210, v210
	v_pk_add_f32 v[184:185], v[136:137], 0 op_sel_hi:[1,0]
	v_pk_add_f32 v[186:187], v[134:135], 0 op_sel_hi:[1,0]
	v_cndmask_b32_e32 v175, v173, v132, vcc
	v_pk_add_f32 v[132:133], v[202:203], 1.0 op_sel_hi:[1,0]
	v_add_f32_e32 v166, v209, v167
	v_add_f32_e32 v167, v213, v211
	v_lshlrev_b32_e32 v174, 2, v130
	v_pk_add_f32 v[130:131], v[204:205], 1.0 op_sel_hi:[1,0]
	v_pk_add_f32 v[200:201], v[200:201], 1.0 op_sel_hi:[1,0]
	v_pk_mul_f32 v[134:135], v[194:195], v[132:133]
	v_pk_mul_f32 v[132:133], v[190:191], v[198:199]
	v_add_f32_e32 v190, v166, v167
	v_pk_mul_f32 v[136:137], v[196:197], v[130:131]
	v_pk_mul_f32 v[130:131], v[192:193], v[200:201]
	v_lshlrev_b32_e32 v175, 2, v175
	s_waitcnt vmcnt(1)
	v_pk_fma_f32 v[166:167], v[184:185], v[88:89], v[178:179]
	v_pk_fma_f32 v[184:185], v[186:187], v[86:87], v[176:177]
	s_waitcnt vmcnt(0)
	v_pk_fma_f32 v[182:183], v[188:189], v[84:85], v[182:183]
	v_pk_fma_f32 v[180:181], v[206:207], v[82:83], v[180:181]
	v_mul_f32_e32 v191, v185, v185
	v_mul_f32_e32 v192, v167, v167
	v_mul_f32_e32 v193, v181, v181
	v_mul_f32_e32 v194, v183, v183
	v_fmac_f32_e32 v191, v184, v184
	v_fmac_f32_e32 v192, v166, v166
	v_fmac_f32_e32 v193, v180, v180
	v_fmac_f32_e32 v194, v182, v182
	v_cvt_pk_bf16_f32 v177, v166, v167
	v_pk_mul_f32 v[186:187], v[136:137], v[166:167]
	v_add_f32_e32 v166, v191, v192
	v_add_f32_e32 v167, v193, v194
	v_add_f32_e32 v166, v166, v167
	v_add_f32_e32 v166, v190, v166
	v_mov_b32_e32 v167, v166
	s_nop 1
	v_permlane16_swap_b32_e32 v166, v167
	v_cvt_pk_bf16_f32 v176, v184, v185
	v_cvt_pk_bf16_f32 v178, v180, v181
	v_cvt_pk_bf16_f32 v179, v182, v183
	v_pk_mul_f32 v[188:189], v[134:135], v[184:185]
	s_waitcnt lgkmcnt(0)
	v_add_f32_e32 v166, v166, v167
	v_mov_b32_e32 v167, v166
	s_nop 1
	v_permlane32_swap_b32_e32 v166, v167
	v_pk_mul_f32 v[182:183], v[130:131], v[182:183]
	v_pk_mul_f32 v[180:181], v[132:133], v[180:181]
	global_store_dwordx4 v[216:217], v[176:179], off offset:256
	s_nop 1
	v_cvt_pk_bf16_f32 v176, v188, v189
	v_cvt_pk_bf16_f32 v177, v186, v187
	v_cvt_pk_bf16_f32 v178, v180, v181
	v_cvt_pk_bf16_f32 v179, v182, v183
	global_store_dwordx4 v[218:219], v[176:179], off offset:256
	s_and_saveexec_b64 s[40:41], s[0:1]
	s_cbranch_execz .LBB0_498
	v_lshlrev_b64 v[176:177], 6, v[156:157]
	v_lshl_add_u64 v[176:177], s[12:13], 0, v[176:177]
	v_lshl_add_u64 v[176:177], s[38:39], 2, v[176:177]
	s_lshl_b32 s8, s72, 2
	v_lshl_add_u64 v[176:177], v[176:177], 0, s[8:9]
	s_waitcnt lgkmcnt(0)
	v_add_f32_e32 v157, v166, v167
	global_store_dword v[176:177], v157, off
.LBB0_498:
	s_or_b64 exec, exec, s[40:41]
	v_or_b32_e32 v166, 16, v156
	s_waitcnt lgkmcnt(0)
	v_ashrrev_i32_e32 v167, 31, v166
	v_lshlrev_b64 v[176:177], 10, v[166:167]
	v_lshl_add_u64 v[184:185], v[176:177], 0, v[154:155]
	v_lshl_add_u64 v[186:187], v[184:185], 2, s[36:37]
	global_load_dwordx4 v[176:179], v[186:187], off
	global_load_dwordx4 v[180:183], v[186:187], off offset:16
	v_pk_add_f32 v[128:129], v[128:129], 0 op_sel_hi:[1,0]
	v_pk_add_f32 v[126:127], v[126:127], 0 op_sel_hi:[1,0]
	v_pk_add_f32 v[124:125], v[124:125], 0 op_sel_hi:[1,0]
	v_pk_add_f32 v[122:123], v[122:123], 0 op_sel_hi:[1,0]
	v_lshlrev_b64 v[184:185], 1, v[184:185]
	v_lshl_add_u64 v[188:189], s[20:21], 0, v[184:185]
	v_lshl_add_u64 v[184:185], s[22:23], 0, v[184:185]
	v_pk_add_f32 v[120:121], v[120:121], 0 op_sel_hi:[1,0]
	v_pk_add_f32 v[118:119], v[118:119], 0 op_sel_hi:[1,0]
	v_pk_add_f32 v[116:117], v[116:117], 0 op_sel_hi:[1,0]
	v_pk_add_f32 v[114:115], v[114:115], 0 op_sel_hi:[1,0]
	s_waitcnt vmcnt(1)
	v_pk_fma_f32 v[178:179], v[128:129], v[80:81], v[178:179]
	v_pk_fma_f32 v[176:177], v[126:127], v[78:79], v[176:177]
	s_waitcnt vmcnt(0)
	v_pk_fma_f32 v[182:183], v[124:125], v[76:77], v[182:183]
	v_pk_fma_f32 v[180:181], v[122:123], v[74:75], v[180:181]
	v_cvt_pk_bf16_f32 v122, v176, v177
	v_cvt_pk_bf16_f32 v123, v178, v179
	v_cvt_pk_bf16_f32 v124, v180, v181
	v_cvt_pk_bf16_f32 v125, v182, v183
	v_pk_mul_f32 v[126:127], v[160:161], v[178:179]
	v_pk_mul_f32 v[128:129], v[164:165], v[176:177]
	v_pk_mul_f32 v[190:191], v[158:159], v[182:183]
	v_pk_mul_f32 v[192:193], v[162:163], v[180:181]
	global_store_dwordx4 v[188:189], v[122:125], off
	v_mul_f32_e32 v157, v177, v177
	v_mul_f32_e32 v177, v179, v179
	v_cvt_pk_bf16_f32 v122, v128, v129
	v_cvt_pk_bf16_f32 v123, v126, v127
	v_cvt_pk_bf16_f32 v124, v192, v193
	v_cvt_pk_bf16_f32 v125, v190, v191
	global_store_dwordx4 v[184:185], v[122:125], off
	global_load_dwordx4 v[122:125], v[186:187], off offset:512
	s_nop 0
	global_load_dwordx4 v[126:129], v[186:187], off offset:528
	v_mul_f32_e32 v179, v181, v181
	v_mul_f32_e32 v181, v183, v183
	v_fmac_f32_e32 v157, v176, v176
	v_fmac_f32_e32 v177, v178, v178
	v_fmac_f32_e32 v179, v180, v180
	v_fmac_f32_e32 v181, v182, v182
	v_add_f32_e32 v157, v157, v177
	v_add_f32_e32 v176, v179, v181
	v_add_f32_e32 v157, v157, v176
	s_waitcnt vmcnt(1)
	v_pk_fma_f32 v[120:121], v[120:121], v[88:89], v[124:125]
	v_pk_fma_f32 v[118:119], v[118:119], v[86:87], v[122:123]
	s_waitcnt vmcnt(0)
	v_pk_fma_f32 v[122:123], v[116:117], v[84:85], v[128:129]
	v_pk_fma_f32 v[124:125], v[114:115], v[82:83], v[126:127]
	v_mul_f32_e32 v126, v119, v119
	v_mul_f32_e32 v127, v121, v121
	v_mul_f32_e32 v128, v125, v125
	v_mul_f32_e32 v129, v123, v123
	v_cvt_pk_bf16_f32 v114, v118, v119
	v_cvt_pk_bf16_f32 v115, v120, v121
	v_cvt_pk_bf16_f32 v116, v124, v125
	v_cvt_pk_bf16_f32 v117, v122, v123
	v_fmac_f32_e32 v126, v118, v118
	v_fmac_f32_e32 v127, v120, v120
	v_fmac_f32_e32 v128, v124, v124
	v_fmac_f32_e32 v129, v122, v122
	global_store_dwordx4 v[188:189], v[114:117], off offset:256
	v_pk_mul_f32 v[120:121], v[136:137], v[120:121]
	v_pk_mul_f32 v[122:123], v[130:131], v[122:123]
	v_add_f32_e32 v114, v126, v127
	v_add_f32_e32 v115, v128, v129
	v_add_f32_e32 v114, v114, v115
	v_add_f32_e32 v117, v157, v114
	v_mov_b32_e32 v126, v117
	s_nop 1
	v_permlane16_swap_b32_e32 v117, v126
	v_pk_mul_f32 v[114:115], v[134:135], v[118:119]
	v_pk_mul_f32 v[118:119], v[132:133], v[124:125]
	v_cvt_pk_bf16_f32 v116, v114, v115
	v_cvt_pk_bf16_f32 v118, v118, v119
	s_waitcnt lgkmcnt(0)
	v_add_f32_e32 v114, v117, v126
	v_mov_b32_e32 v115, v114
	s_nop 1
	v_permlane32_swap_b32_e32 v114, v115
	v_cvt_pk_bf16_f32 v117, v120, v121
	v_cvt_pk_bf16_f32 v119, v122, v123
	global_store_dwordx4 v[184:185], v[116:119], off offset:256
	s_and_saveexec_b64 s[40:41], s[0:1]
	s_cbranch_execz .LBB0_500
	v_lshlrev_b64 v[116:117], 6, v[166:167]
	v_lshl_add_u64 v[116:117], s[12:13], 0, v[116:117]
	v_lshl_add_u64 v[116:117], s[38:39], 2, v[116:117]
	s_lshl_b32 s8, s72, 2
	v_lshl_add_u64 v[116:117], v[116:117], 0, s[8:9]
	s_waitcnt lgkmcnt(0)
	v_add_f32_e32 v114, v114, v115
	global_store_dword v[116:117], v114, off
.LBB0_500:
	s_or_b64 exec, exec, s[40:41]
	v_or_b32_e32 v114, 32, v156
	s_waitcnt lgkmcnt(0)
	v_ashrrev_i32_e32 v115, 31, v114
	v_lshlrev_b64 v[116:117], 10, v[114:115]
	v_lshl_add_u64 v[124:125], v[116:117], 0, v[154:155]
	v_lshl_add_u64 v[126:127], v[124:125], 2, s[36:37]
	global_load_dwordx4 v[116:119], v[126:127], off
	global_load_dwordx4 v[120:123], v[126:127], off offset:16
	v_pk_add_f32 v[112:113], v[112:113], 0 op_sel_hi:[1,0]
	v_pk_add_f32 v[110:111], v[110:111], 0 op_sel_hi:[1,0]
	v_pk_add_f32 v[108:109], v[108:109], 0 op_sel_hi:[1,0]
	v_pk_add_f32 v[106:107], v[106:107], 0 op_sel_hi:[1,0]
	v_lshlrev_b64 v[124:125], 1, v[124:125]
	v_lshl_add_u64 v[128:129], s[20:21], 0, v[124:125]
	v_lshl_add_u64 v[124:125], s[22:23], 0, v[124:125]
	v_pk_add_f32 v[104:105], v[104:105], 0 op_sel_hi:[1,0]
	v_pk_add_f32 v[102:103], v[102:103], 0 op_sel_hi:[1,0]
	v_pk_add_f32 v[100:101], v[100:101], 0 op_sel_hi:[1,0]
	v_pk_add_f32 v[98:99], v[98:99], 0 op_sel_hi:[1,0]
	s_waitcnt vmcnt(1)
	v_pk_fma_f32 v[118:119], v[112:113], v[80:81], v[118:119]
	v_pk_fma_f32 v[116:117], v[110:111], v[78:79], v[116:117]
	s_waitcnt vmcnt(0)
	v_pk_fma_f32 v[122:123], v[108:109], v[76:77], v[122:123]
	v_pk_fma_f32 v[120:121], v[106:107], v[74:75], v[120:121]
	v_cvt_pk_bf16_f32 v106, v116, v117
	v_cvt_pk_bf16_f32 v107, v118, v119
	v_cvt_pk_bf16_f32 v108, v120, v121
	v_cvt_pk_bf16_f32 v109, v122, v123
	v_pk_mul_f32 v[110:111], v[160:161], v[118:119]
	v_pk_mul_f32 v[112:113], v[164:165], v[116:117]
	v_pk_mul_f32 v[166:167], v[158:159], v[122:123]
	v_pk_mul_f32 v[176:177], v[162:163], v[120:121]
	global_store_dwordx4 v[128:129], v[106:109], off
	v_mul_f32_e32 v117, v117, v117
	v_mul_f32_e32 v119, v119, v119
	v_cvt_pk_bf16_f32 v106, v112, v113
	v_cvt_pk_bf16_f32 v107, v110, v111
	v_cvt_pk_bf16_f32 v108, v176, v177
	v_cvt_pk_bf16_f32 v109, v166, v167
	global_store_dwordx4 v[124:125], v[106:109], off
	global_load_dwordx4 v[106:109], v[126:127], off offset:512
	s_nop 0
	global_load_dwordx4 v[110:113], v[126:127], off offset:528
	v_mul_f32_e32 v121, v121, v121
	v_mul_f32_e32 v123, v123, v123
	v_fmac_f32_e32 v117, v116, v116
	v_fmac_f32_e32 v119, v118, v118
	v_fmac_f32_e32 v121, v120, v120
	v_fmac_f32_e32 v123, v122, v122
	v_add_f32_e32 v116, v117, v119
	v_add_f32_e32 v117, v121, v123
	v_add_f32_e32 v116, v116, v117
	s_waitcnt vmcnt(1)
	v_pk_fma_f32 v[104:105], v[104:105], v[88:89], v[108:109]
	v_pk_fma_f32 v[102:103], v[102:103], v[86:87], v[106:107]
	s_waitcnt vmcnt(0)
	v_pk_fma_f32 v[106:107], v[100:101], v[84:85], v[112:113]
	v_pk_fma_f32 v[108:109], v[98:99], v[82:83], v[110:111]
	v_mul_f32_e32 v110, v103, v103
	v_mul_f32_e32 v111, v105, v105
	v_mul_f32_e32 v112, v109, v109
	v_mul_f32_e32 v113, v107, v107
	v_cvt_pk_bf16_f32 v98, v102, v103
	v_cvt_pk_bf16_f32 v99, v104, v105
	v_cvt_pk_bf16_f32 v100, v108, v109
	v_cvt_pk_bf16_f32 v101, v106, v107
	v_fmac_f32_e32 v110, v102, v102
	v_fmac_f32_e32 v111, v104, v104
	v_fmac_f32_e32 v112, v108, v108
	v_fmac_f32_e32 v113, v106, v106
	global_store_dwordx4 v[128:129], v[98:101], off offset:256
	v_pk_mul_f32 v[104:105], v[136:137], v[104:105]
	v_pk_mul_f32 v[106:107], v[130:131], v[106:107]
	v_add_f32_e32 v98, v110, v111
	v_add_f32_e32 v99, v112, v113
	v_add_f32_e32 v98, v98, v99
	v_add_f32_e32 v101, v116, v98
	v_mov_b32_e32 v110, v101
	s_nop 1
	v_permlane16_swap_b32_e32 v101, v110
	v_pk_mul_f32 v[98:99], v[134:135], v[102:103]
	v_pk_mul_f32 v[102:103], v[132:133], v[108:109]
	v_cvt_pk_bf16_f32 v100, v98, v99
	v_cvt_pk_bf16_f32 v102, v102, v103
	s_waitcnt lgkmcnt(0)
	v_add_f32_e32 v98, v101, v110
	v_mov_b32_e32 v99, v98
	s_nop 1
	v_permlane32_swap_b32_e32 v98, v99
	v_cvt_pk_bf16_f32 v101, v104, v105
	v_cvt_pk_bf16_f32 v103, v106, v107
	global_store_dwordx4 v[124:125], v[100:103], off offset:256
	s_and_saveexec_b64 s[40:41], s[0:1]
	s_cbranch_execz .LBB0_502
	v_lshlrev_b64 v[100:101], 6, v[114:115]
	v_lshl_add_u64 v[100:101], s[12:13], 0, v[100:101]
	v_lshl_add_u64 v[100:101], s[38:39], 2, v[100:101]
	s_lshl_b32 s8, s72, 2
	v_lshl_add_u64 v[100:101], v[100:101], 0, s[8:9]
	s_waitcnt lgkmcnt(0)
	v_add_f32_e32 v98, v98, v99
	global_store_dword v[100:101], v98, off
.LBB0_502:
	s_or_b64 exec, exec, s[40:41]
	v_or_b32_e32 v98, 48, v156
	s_waitcnt lgkmcnt(0)
	v_ashrrev_i32_e32 v99, 31, v98
	v_lshlrev_b64 v[100:101], 10, v[98:99]
	v_lshl_add_u64 v[108:109], v[100:101], 0, v[154:155]
	v_lshl_add_u64 v[110:111], v[108:109], 2, s[36:37]
	global_load_dwordx4 v[100:103], v[110:111], off
	global_load_dwordx4 v[104:107], v[110:111], off offset:16
	v_pk_add_f32 v[96:97], v[96:97], 0 op_sel_hi:[1,0]
	v_pk_add_f32 v[94:95], v[94:95], 0 op_sel_hi:[1,0]
	v_pk_add_f32 v[92:93], v[92:93], 0 op_sel_hi:[1,0]
	v_pk_add_f32 v[90:91], v[90:91], 0 op_sel_hi:[1,0]
	v_lshlrev_b64 v[108:109], 1, v[108:109]
	v_lshl_add_u64 v[112:113], s[20:21], 0, v[108:109]
	v_lshl_add_u64 v[108:109], s[22:23], 0, v[108:109]
	v_pk_add_f32 v[72:73], v[72:73], 0 op_sel_hi:[1,0]
	v_pk_add_f32 v[70:71], v[70:71], 0 op_sel_hi:[1,0]
	v_pk_add_f32 v[68:69], v[68:69], 0 op_sel_hi:[1,0]
	v_pk_add_f32 v[66:67], v[66:67], 0 op_sel_hi:[1,0]
	s_waitcnt vmcnt(1)
	v_pk_fma_f32 v[102:103], v[96:97], v[80:81], v[102:103]
	v_pk_fma_f32 v[100:101], v[94:95], v[78:79], v[100:101]
	s_waitcnt vmcnt(0)
	v_pk_fma_f32 v[106:107], v[92:93], v[76:77], v[106:107]
	v_pk_fma_f32 v[104:105], v[90:91], v[74:75], v[104:105]
	v_cvt_pk_bf16_f32 v90, v100, v101
	v_cvt_pk_bf16_f32 v91, v102, v103
	v_cvt_pk_bf16_f32 v92, v104, v105
	v_cvt_pk_bf16_f32 v93, v106, v107
	v_pk_mul_f32 v[94:95], v[160:161], v[102:103]
	v_pk_mul_f32 v[96:97], v[164:165], v[100:101]
	v_pk_mul_f32 v[114:115], v[158:159], v[106:107]
	v_pk_mul_f32 v[116:117], v[162:163], v[104:105]
	global_store_dwordx4 v[112:113], v[90:93], off
	v_mul_f32_e32 v101, v101, v101
	v_mul_f32_e32 v103, v103, v103
	v_cvt_pk_bf16_f32 v90, v96, v97
	v_cvt_pk_bf16_f32 v91, v94, v95
	v_cvt_pk_bf16_f32 v92, v116, v117
	v_cvt_pk_bf16_f32 v93, v114, v115
	global_store_dwordx4 v[108:109], v[90:93], off
	global_load_dwordx4 v[90:93], v[110:111], off offset:512
	s_nop 0
	global_load_dwordx4 v[94:97], v[110:111], off offset:528
	v_mul_f32_e32 v105, v105, v105
	v_mul_f32_e32 v107, v107, v107
	v_fmac_f32_e32 v101, v100, v100
	v_fmac_f32_e32 v103, v102, v102
	v_fmac_f32_e32 v105, v104, v104
	v_fmac_f32_e32 v107, v106, v106
	v_add_f32_e32 v100, v101, v103
	v_add_f32_e32 v101, v105, v107
	v_add_f32_e32 v100, v100, v101
	s_waitcnt vmcnt(1)
	v_pk_fma_f32 v[72:73], v[72:73], v[88:89], v[92:93]
	v_pk_fma_f32 v[70:71], v[70:71], v[86:87], v[90:91]
	s_waitcnt vmcnt(0)
	v_pk_fma_f32 v[90:91], v[68:69], v[84:85], v[96:97]
	v_pk_fma_f32 v[92:93], v[66:67], v[82:83], v[94:95]
	v_mul_f32_e32 v94, v71, v71
	v_mul_f32_e32 v95, v73, v73
	v_mul_f32_e32 v96, v93, v93
	v_mul_f32_e32 v97, v91, v91
	v_cvt_pk_bf16_f32 v66, v70, v71
	v_cvt_pk_bf16_f32 v67, v72, v73
	v_cvt_pk_bf16_f32 v68, v92, v93
	v_cvt_pk_bf16_f32 v69, v90, v91
	v_fmac_f32_e32 v94, v70, v70
	v_fmac_f32_e32 v95, v72, v72
	v_fmac_f32_e32 v96, v92, v92
	v_fmac_f32_e32 v97, v90, v90
	global_store_dwordx4 v[112:113], v[66:69], off offset:256
	v_pk_mul_f32 v[72:73], v[136:137], v[72:73]
	v_pk_mul_f32 v[90:91], v[130:131], v[90:91]
	v_add_f32_e32 v66, v94, v95
	v_add_f32_e32 v67, v96, v97
	v_add_f32_e32 v66, v66, v67
	v_add_f32_e32 v69, v100, v66
	v_mov_b32_e32 v94, v69
	s_nop 1
	v_permlane16_swap_b32_e32 v69, v94
	v_pk_mul_f32 v[66:67], v[134:135], v[70:71]
	v_pk_mul_f32 v[70:71], v[132:133], v[92:93]
	v_cvt_pk_bf16_f32 v68, v66, v67
	v_cvt_pk_bf16_f32 v70, v70, v71
	s_waitcnt lgkmcnt(0)
	v_add_f32_e32 v66, v69, v94
	v_mov_b32_e32 v67, v66
	s_nop 1
	v_permlane32_swap_b32_e32 v66, v67
	v_cvt_pk_bf16_f32 v69, v72, v73
	v_cvt_pk_bf16_f32 v71, v90, v91
	global_store_dwordx4 v[108:109], v[68:71], off offset:256
	s_and_saveexec_b64 s[40:41], s[0:1]
	s_cbranch_execz .LBB0_504
	v_lshlrev_b64 v[68:69], 6, v[98:99]
	v_lshl_add_u64 v[68:69], s[12:13], 0, v[68:69]
	v_lshl_add_u64 v[68:69], s[38:39], 2, v[68:69]
	s_lshl_b32 s8, s72, 2
	v_lshl_add_u64 v[68:69], v[68:69], 0, s[8:9]
	s_waitcnt lgkmcnt(0)
	v_add_f32_e32 v66, v66, v67
	global_store_dword v[68:69], v66, off
.LBB0_504:
	s_or_b64 exec, exec, s[40:41]
	v_add_u32_e32 v66, 0x80, v156
	s_waitcnt lgkmcnt(0)
	v_ashrrev_i32_e32 v67, 31, v66
	v_lshlrev_b64 v[68:69], 10, v[66:67]
	v_lshl_add_u64 v[72:73], v[68:69], 0, v[154:155]
	v_lshl_add_u64 v[94:95], v[72:73], 2, s[36:37]
	global_load_dwordx4 v[68:71], v[94:95], off
	global_load_dwordx4 v[90:93], v[94:95], off offset:16
	v_pk_add_f32 v[64:65], v[64:65], 0 op_sel_hi:[1,0]
	v_pk_add_f32 v[62:63], v[62:63], 0 op_sel_hi:[1,0]
	v_pk_add_f32 v[60:61], v[60:61], 0 op_sel_hi:[1,0]
	v_pk_add_f32 v[58:59], v[58:59], 0 op_sel_hi:[1,0]
	v_lshlrev_b64 v[72:73], 1, v[72:73]
	v_lshl_add_u64 v[96:97], s[20:21], 0, v[72:73]
	v_lshl_add_u64 v[72:73], s[22:23], 0, v[72:73]
	v_pk_add_f32 v[56:57], v[56:57], 0 op_sel_hi:[1,0]
	v_pk_add_f32 v[54:55], v[54:55], 0 op_sel_hi:[1,0]
	v_pk_add_f32 v[52:53], v[52:53], 0 op_sel_hi:[1,0]
	v_pk_add_f32 v[50:51], v[50:51], 0 op_sel_hi:[1,0]
	s_waitcnt vmcnt(1)
	v_pk_fma_f32 v[70:71], v[64:65], v[80:81], v[70:71]
	v_pk_fma_f32 v[68:69], v[62:63], v[78:79], v[68:69]
	s_waitcnt vmcnt(0)
	v_pk_fma_f32 v[92:93], v[60:61], v[76:77], v[92:93]
	v_pk_fma_f32 v[90:91], v[58:59], v[74:75], v[90:91]
	v_cvt_pk_bf16_f32 v58, v68, v69
	v_cvt_pk_bf16_f32 v59, v70, v71
	v_cvt_pk_bf16_f32 v60, v90, v91
	v_cvt_pk_bf16_f32 v61, v92, v93
	v_pk_mul_f32 v[62:63], v[160:161], v[70:71]
	v_pk_mul_f32 v[64:65], v[164:165], v[68:69]
	v_pk_mul_f32 v[98:99], v[158:159], v[92:93]
	v_pk_mul_f32 v[100:101], v[162:163], v[90:91]
	global_store_dwordx4 v[96:97], v[58:61], off
	v_mul_f32_e32 v69, v69, v69
	v_mul_f32_e32 v71, v71, v71
	v_cvt_pk_bf16_f32 v58, v64, v65
	v_cvt_pk_bf16_f32 v59, v62, v63
	v_cvt_pk_bf16_f32 v60, v100, v101
	v_cvt_pk_bf16_f32 v61, v98, v99
	global_store_dwordx4 v[72:73], v[58:61], off
	global_load_dwordx4 v[58:61], v[94:95], off offset:512
	s_nop 0
	global_load_dwordx4 v[62:65], v[94:95], off offset:528
	v_mul_f32_e32 v91, v91, v91
	v_mul_f32_e32 v93, v93, v93
	v_fmac_f32_e32 v69, v68, v68
	v_fmac_f32_e32 v71, v70, v70
	v_fmac_f32_e32 v91, v90, v90
	v_fmac_f32_e32 v93, v92, v92
	v_add_f32_e32 v68, v69, v71
	v_add_f32_e32 v69, v91, v93
	v_add_f32_e32 v68, v68, v69
	s_waitcnt vmcnt(1)
	v_pk_fma_f32 v[56:57], v[56:57], v[88:89], v[60:61]
	v_pk_fma_f32 v[54:55], v[54:55], v[86:87], v[58:59]
	s_waitcnt vmcnt(0)
	v_pk_fma_f32 v[58:59], v[52:53], v[84:85], v[64:65]
	v_pk_fma_f32 v[60:61], v[50:51], v[82:83], v[62:63]
	v_mul_f32_e32 v62, v55, v55
	v_mul_f32_e32 v63, v57, v57
	v_mul_f32_e32 v64, v61, v61
	v_mul_f32_e32 v65, v59, v59
	v_cvt_pk_bf16_f32 v50, v54, v55
	v_cvt_pk_bf16_f32 v51, v56, v57
	v_cvt_pk_bf16_f32 v52, v60, v61
	v_cvt_pk_bf16_f32 v53, v58, v59
	v_fmac_f32_e32 v62, v54, v54
	v_fmac_f32_e32 v63, v56, v56
	v_fmac_f32_e32 v64, v60, v60
	v_fmac_f32_e32 v65, v58, v58
	global_store_dwordx4 v[96:97], v[50:53], off offset:256
	v_pk_mul_f32 v[56:57], v[136:137], v[56:57]
	v_pk_mul_f32 v[58:59], v[130:131], v[58:59]
	v_add_f32_e32 v50, v62, v63
	v_add_f32_e32 v51, v64, v65
	v_add_f32_e32 v50, v50, v51
	v_add_f32_e32 v53, v68, v50
	v_mov_b32_e32 v62, v53
	s_nop 1
	v_permlane16_swap_b32_e32 v53, v62
	v_pk_mul_f32 v[50:51], v[134:135], v[54:55]
	v_pk_mul_f32 v[54:55], v[132:133], v[60:61]
	v_cvt_pk_bf16_f32 v52, v50, v51
	v_cvt_pk_bf16_f32 v54, v54, v55
	s_waitcnt lgkmcnt(0)
	v_add_f32_e32 v50, v53, v62
	v_mov_b32_e32 v51, v50
	s_nop 1
	v_permlane32_swap_b32_e32 v50, v51
	v_cvt_pk_bf16_f32 v53, v56, v57
	v_cvt_pk_bf16_f32 v55, v58, v59
	global_store_dwordx4 v[72:73], v[52:55], off offset:256
	s_and_saveexec_b64 s[40:41], s[0:1]
	s_cbranch_execz .LBB0_506
	v_lshlrev_b64 v[52:53], 6, v[66:67]
	v_lshl_add_u64 v[52:53], s[12:13], 0, v[52:53]
	v_lshl_add_u64 v[52:53], s[38:39], 2, v[52:53]
	s_lshl_b32 s8, s72, 2
	v_lshl_add_u64 v[52:53], v[52:53], 0, s[8:9]
	s_waitcnt lgkmcnt(0)
	v_add_f32_e32 v50, v50, v51
	global_store_dword v[52:53], v50, off
.LBB0_506:
	s_or_b64 exec, exec, s[40:41]
	v_add_u32_e32 v50, 0x90, v156
	s_waitcnt lgkmcnt(0)
	v_ashrrev_i32_e32 v51, 31, v50
	v_lshlrev_b64 v[52:53], 10, v[50:51]
	v_lshl_add_u64 v[60:61], v[52:53], 0, v[154:155]
	v_lshl_add_u64 v[62:63], v[60:61], 2, s[36:37]
	global_load_dwordx4 v[52:55], v[62:63], off
	global_load_dwordx4 v[56:59], v[62:63], off offset:16
	v_pk_add_f32 v[48:49], v[48:49], 0 op_sel_hi:[1,0]
	v_pk_add_f32 v[46:47], v[46:47], 0 op_sel_hi:[1,0]
	v_pk_add_f32 v[44:45], v[44:45], 0 op_sel_hi:[1,0]
	v_pk_add_f32 v[42:43], v[42:43], 0 op_sel_hi:[1,0]
	v_lshlrev_b64 v[60:61], 1, v[60:61]
	v_lshl_add_u64 v[64:65], s[20:21], 0, v[60:61]
	v_lshl_add_u64 v[60:61], s[22:23], 0, v[60:61]
	v_pk_add_f32 v[40:41], v[40:41], 0 op_sel_hi:[1,0]
	v_pk_add_f32 v[38:39], v[38:39], 0 op_sel_hi:[1,0]
	v_pk_add_f32 v[36:37], v[36:37], 0 op_sel_hi:[1,0]
	v_pk_add_f32 v[34:35], v[34:35], 0 op_sel_hi:[1,0]
	s_waitcnt vmcnt(1)
	v_pk_fma_f32 v[54:55], v[48:49], v[80:81], v[54:55]
	v_pk_fma_f32 v[52:53], v[46:47], v[78:79], v[52:53]
	s_waitcnt vmcnt(0)
	v_pk_fma_f32 v[58:59], v[44:45], v[76:77], v[58:59]
	v_pk_fma_f32 v[56:57], v[42:43], v[74:75], v[56:57]
	v_cvt_pk_bf16_f32 v42, v52, v53
	v_cvt_pk_bf16_f32 v43, v54, v55
	v_cvt_pk_bf16_f32 v44, v56, v57
	v_cvt_pk_bf16_f32 v45, v58, v59
	v_pk_mul_f32 v[46:47], v[160:161], v[54:55]
	v_pk_mul_f32 v[48:49], v[164:165], v[52:53]
	v_pk_mul_f32 v[66:67], v[158:159], v[58:59]
	v_pk_mul_f32 v[68:69], v[162:163], v[56:57]
	global_store_dwordx4 v[64:65], v[42:45], off
	v_mul_f32_e32 v53, v53, v53
	v_mul_f32_e32 v55, v55, v55
	v_cvt_pk_bf16_f32 v42, v48, v49
	v_cvt_pk_bf16_f32 v43, v46, v47
	v_cvt_pk_bf16_f32 v44, v68, v69
	v_cvt_pk_bf16_f32 v45, v66, v67
	global_store_dwordx4 v[60:61], v[42:45], off
	global_load_dwordx4 v[42:45], v[62:63], off offset:512
	s_nop 0
	global_load_dwordx4 v[46:49], v[62:63], off offset:528
	v_mul_f32_e32 v57, v57, v57
	v_mul_f32_e32 v59, v59, v59
	v_fmac_f32_e32 v53, v52, v52
	v_fmac_f32_e32 v55, v54, v54
	v_fmac_f32_e32 v57, v56, v56
	v_fmac_f32_e32 v59, v58, v58
	v_add_f32_e32 v52, v53, v55
	v_add_f32_e32 v53, v57, v59
	v_add_f32_e32 v52, v52, v53
	s_waitcnt vmcnt(1)
	v_pk_fma_f32 v[40:41], v[40:41], v[88:89], v[44:45]
	v_pk_fma_f32 v[38:39], v[38:39], v[86:87], v[42:43]
	s_waitcnt vmcnt(0)
	v_pk_fma_f32 v[42:43], v[36:37], v[84:85], v[48:49]
	v_pk_fma_f32 v[44:45], v[34:35], v[82:83], v[46:47]
	v_mul_f32_e32 v46, v39, v39
	v_mul_f32_e32 v47, v41, v41
	v_mul_f32_e32 v48, v45, v45
	v_mul_f32_e32 v49, v43, v43
	v_cvt_pk_bf16_f32 v34, v38, v39
	v_cvt_pk_bf16_f32 v35, v40, v41
	v_cvt_pk_bf16_f32 v36, v44, v45
	v_cvt_pk_bf16_f32 v37, v42, v43
	v_fmac_f32_e32 v46, v38, v38
	v_fmac_f32_e32 v47, v40, v40
	v_fmac_f32_e32 v48, v44, v44
	v_fmac_f32_e32 v49, v42, v42
	global_store_dwordx4 v[64:65], v[34:37], off offset:256
	v_pk_mul_f32 v[40:41], v[136:137], v[40:41]
	v_pk_mul_f32 v[42:43], v[130:131], v[42:43]
	v_add_f32_e32 v34, v46, v47
	v_add_f32_e32 v35, v48, v49
	v_add_f32_e32 v34, v34, v35
	v_add_f32_e32 v37, v52, v34
	v_mov_b32_e32 v46, v37
	s_nop 1
	v_permlane16_swap_b32_e32 v37, v46
	v_pk_mul_f32 v[34:35], v[134:135], v[38:39]
	v_pk_mul_f32 v[38:39], v[132:133], v[44:45]
	v_cvt_pk_bf16_f32 v36, v34, v35
	v_cvt_pk_bf16_f32 v38, v38, v39
	s_waitcnt lgkmcnt(0)
	v_add_f32_e32 v34, v37, v46
	v_mov_b32_e32 v35, v34
	s_nop 1
	v_permlane32_swap_b32_e32 v34, v35
	v_cvt_pk_bf16_f32 v37, v40, v41
	v_cvt_pk_bf16_f32 v39, v42, v43
	global_store_dwordx4 v[60:61], v[36:39], off offset:256
	s_and_saveexec_b64 s[40:41], s[0:1]
	s_cbranch_execz .LBB0_508
	v_lshlrev_b64 v[36:37], 6, v[50:51]
	v_lshl_add_u64 v[36:37], s[12:13], 0, v[36:37]
	v_lshl_add_u64 v[36:37], s[38:39], 2, v[36:37]
	s_lshl_b32 s8, s72, 2
	v_lshl_add_u64 v[36:37], v[36:37], 0, s[8:9]
	s_waitcnt lgkmcnt(0)
	v_add_f32_e32 v34, v34, v35
	global_store_dword v[36:37], v34, off
.LBB0_508:
	s_or_b64 exec, exec, s[40:41]
	v_add_u32_e32 v34, 0xa0, v156
	s_waitcnt lgkmcnt(0)
	v_ashrrev_i32_e32 v35, 31, v34
	v_lshlrev_b64 v[36:37], 10, v[34:35]
	v_lshl_add_u64 v[44:45], v[36:37], 0, v[154:155]
	v_lshl_add_u64 v[46:47], v[44:45], 2, s[36:37]
	global_load_dwordx4 v[36:39], v[46:47], off
	global_load_dwordx4 v[40:43], v[46:47], off offset:16
	v_pk_add_f32 v[32:33], v[32:33], 0 op_sel_hi:[1,0]
	v_pk_add_f32 v[30:31], v[30:31], 0 op_sel_hi:[1,0]
	v_pk_add_f32 v[28:29], v[28:29], 0 op_sel_hi:[1,0]
	v_pk_add_f32 v[26:27], v[26:27], 0 op_sel_hi:[1,0]
	v_lshlrev_b64 v[44:45], 1, v[44:45]
	v_lshl_add_u64 v[48:49], s[20:21], 0, v[44:45]
	v_lshl_add_u64 v[44:45], s[22:23], 0, v[44:45]
	v_pk_add_f32 v[24:25], v[24:25], 0 op_sel_hi:[1,0]
	v_pk_add_f32 v[22:23], v[22:23], 0 op_sel_hi:[1,0]
	v_pk_add_f32 v[20:21], v[20:21], 0 op_sel_hi:[1,0]
	v_pk_add_f32 v[18:19], v[18:19], 0 op_sel_hi:[1,0]
	s_waitcnt vmcnt(1)
	v_pk_fma_f32 v[38:39], v[32:33], v[80:81], v[38:39]
	v_pk_fma_f32 v[36:37], v[30:31], v[78:79], v[36:37]
	s_waitcnt vmcnt(0)
	v_pk_fma_f32 v[42:43], v[28:29], v[76:77], v[42:43]
	v_pk_fma_f32 v[40:41], v[26:27], v[74:75], v[40:41]
	v_cvt_pk_bf16_f32 v26, v36, v37
	v_cvt_pk_bf16_f32 v27, v38, v39
	v_cvt_pk_bf16_f32 v28, v40, v41
	v_cvt_pk_bf16_f32 v29, v42, v43
	v_pk_mul_f32 v[30:31], v[160:161], v[38:39]
	v_pk_mul_f32 v[32:33], v[164:165], v[36:37]
	v_pk_mul_f32 v[50:51], v[158:159], v[42:43]
	v_pk_mul_f32 v[52:53], v[162:163], v[40:41]
	global_store_dwordx4 v[48:49], v[26:29], off
	v_mul_f32_e32 v37, v37, v37
	v_mul_f32_e32 v39, v39, v39
	v_cvt_pk_bf16_f32 v26, v32, v33
	v_cvt_pk_bf16_f32 v27, v30, v31
	v_cvt_pk_bf16_f32 v28, v52, v53
	v_cvt_pk_bf16_f32 v29, v50, v51
	global_store_dwordx4 v[44:45], v[26:29], off
	global_load_dwordx4 v[26:29], v[46:47], off offset:512
	s_nop 0
	global_load_dwordx4 v[30:33], v[46:47], off offset:528
	v_mul_f32_e32 v41, v41, v41
	v_mul_f32_e32 v43, v43, v43
	v_fmac_f32_e32 v37, v36, v36
	v_fmac_f32_e32 v39, v38, v38
	v_fmac_f32_e32 v41, v40, v40
	v_fmac_f32_e32 v43, v42, v42
	v_add_f32_e32 v36, v37, v39
	v_add_f32_e32 v37, v41, v43
	v_add_f32_e32 v36, v36, v37
	s_waitcnt vmcnt(1)
	v_pk_fma_f32 v[24:25], v[24:25], v[88:89], v[28:29]
	v_pk_fma_f32 v[22:23], v[22:23], v[86:87], v[26:27]
	s_waitcnt vmcnt(0)
	v_pk_fma_f32 v[26:27], v[20:21], v[84:85], v[32:33]
	v_pk_fma_f32 v[28:29], v[18:19], v[82:83], v[30:31]
	v_mul_f32_e32 v30, v23, v23
	v_mul_f32_e32 v31, v25, v25
	v_mul_f32_e32 v32, v29, v29
	v_mul_f32_e32 v33, v27, v27
	v_cvt_pk_bf16_f32 v18, v22, v23
	v_cvt_pk_bf16_f32 v19, v24, v25
	v_cvt_pk_bf16_f32 v20, v28, v29
	v_cvt_pk_bf16_f32 v21, v26, v27
	v_fmac_f32_e32 v30, v22, v22
	v_fmac_f32_e32 v31, v24, v24
	v_fmac_f32_e32 v32, v28, v28
	v_fmac_f32_e32 v33, v26, v26
	global_store_dwordx4 v[48:49], v[18:21], off offset:256
	v_pk_mul_f32 v[24:25], v[136:137], v[24:25]
	v_pk_mul_f32 v[26:27], v[130:131], v[26:27]
	v_add_f32_e32 v18, v30, v31
	v_add_f32_e32 v19, v32, v33
	v_add_f32_e32 v18, v18, v19
	v_add_f32_e32 v21, v36, v18
	v_mov_b32_e32 v30, v21
	s_nop 1
	v_permlane16_swap_b32_e32 v21, v30
	v_pk_mul_f32 v[18:19], v[134:135], v[22:23]
	v_pk_mul_f32 v[22:23], v[132:133], v[28:29]
	v_cvt_pk_bf16_f32 v20, v18, v19
	v_cvt_pk_bf16_f32 v22, v22, v23
	s_waitcnt lgkmcnt(0)
	v_add_f32_e32 v18, v21, v30
	v_mov_b32_e32 v19, v18
	s_nop 1
	v_permlane32_swap_b32_e32 v18, v19
	v_cvt_pk_bf16_f32 v21, v24, v25
	v_cvt_pk_bf16_f32 v23, v26, v27
	global_store_dwordx4 v[44:45], v[20:23], off offset:256
	s_and_saveexec_b64 s[40:41], s[0:1]
	s_cbranch_execz .LBB0_510
	v_lshlrev_b64 v[20:21], 6, v[34:35]
	v_lshl_add_u64 v[20:21], s[12:13], 0, v[20:21]
	v_lshl_add_u64 v[20:21], s[38:39], 2, v[20:21]
	s_lshl_b32 s8, s72, 2
	v_lshl_add_u64 v[20:21], v[20:21], 0, s[8:9]
	s_waitcnt lgkmcnt(0)
	v_add_f32_e32 v18, v18, v19
	global_store_dword v[20:21], v18, off
.LBB0_510:
	s_or_b64 exec, exec, s[40:41]
	v_add_u32_e32 v18, 0xb0, v156
	s_waitcnt lgkmcnt(0)
	v_ashrrev_i32_e32 v19, 31, v18
	v_lshlrev_b64 v[20:21], 10, v[18:19]
	v_lshl_add_u64 v[28:29], v[20:21], 0, v[154:155]
	v_lshl_add_u64 v[30:31], v[28:29], 2, s[36:37]
	global_load_dwordx4 v[20:23], v[30:31], off
	global_load_dwordx4 v[24:27], v[30:31], off offset:16
	v_pk_add_f32 v[16:17], v[16:17], 0 op_sel_hi:[1,0]
	v_pk_add_f32 v[14:15], v[14:15], 0 op_sel_hi:[1,0]
	v_pk_add_f32 v[12:13], v[12:13], 0 op_sel_hi:[1,0]
	v_pk_add_f32 v[10:11], v[10:11], 0 op_sel_hi:[1,0]
	v_lshlrev_b64 v[28:29], 1, v[28:29]
	v_lshl_add_u64 v[32:33], s[20:21], 0, v[28:29]
	v_lshl_add_u64 v[28:29], s[22:23], 0, v[28:29]
	v_pk_add_f32 v[8:9], v[8:9], 0 op_sel_hi:[1,0]
	v_pk_add_f32 v[6:7], v[6:7], 0 op_sel_hi:[1,0]
	v_pk_add_f32 v[4:5], v[4:5], 0 op_sel_hi:[1,0]
	v_pk_add_f32 v[2:3], v[2:3], 0 op_sel_hi:[1,0]
	s_waitcnt vmcnt(1)
	v_pk_fma_f32 v[22:23], v[16:17], v[80:81], v[22:23]
	v_pk_fma_f32 v[20:21], v[14:15], v[78:79], v[20:21]
	s_waitcnt vmcnt(0)
	v_pk_fma_f32 v[26:27], v[12:13], v[76:77], v[26:27]
	v_pk_fma_f32 v[24:25], v[10:11], v[74:75], v[24:25]
	v_cvt_pk_bf16_f32 v10, v20, v21
	v_cvt_pk_bf16_f32 v11, v22, v23
	v_cvt_pk_bf16_f32 v12, v24, v25
	v_cvt_pk_bf16_f32 v13, v26, v27
	v_pk_mul_f32 v[14:15], v[160:161], v[22:23]
	v_pk_mul_f32 v[16:17], v[164:165], v[20:21]
	v_pk_mul_f32 v[34:35], v[158:159], v[26:27]
	v_pk_mul_f32 v[36:37], v[162:163], v[24:25]
	global_store_dwordx4 v[32:33], v[10:13], off
	v_mul_f32_e32 v21, v21, v21
	v_mul_f32_e32 v23, v23, v23
	v_cvt_pk_bf16_f32 v10, v16, v17
	v_cvt_pk_bf16_f32 v11, v14, v15
	v_cvt_pk_bf16_f32 v12, v36, v37
	v_cvt_pk_bf16_f32 v13, v34, v35
	global_store_dwordx4 v[28:29], v[10:13], off
	global_load_dwordx4 v[10:13], v[30:31], off offset:512
	s_nop 0
	global_load_dwordx4 v[14:17], v[30:31], off offset:528
	v_mul_f32_e32 v25, v25, v25
	v_mul_f32_e32 v27, v27, v27
	v_fmac_f32_e32 v21, v20, v20
	v_fmac_f32_e32 v23, v22, v22
	v_fmac_f32_e32 v25, v24, v24
	v_fmac_f32_e32 v27, v26, v26
	v_add_f32_e32 v20, v21, v23
	v_add_f32_e32 v21, v25, v27
	v_add_f32_e32 v20, v20, v21
	s_waitcnt vmcnt(1)
	v_pk_fma_f32 v[8:9], v[8:9], v[88:89], v[12:13]
	v_pk_fma_f32 v[6:7], v[6:7], v[86:87], v[10:11]
	s_waitcnt vmcnt(0)
	v_pk_fma_f32 v[10:11], v[4:5], v[84:85], v[16:17]
	v_pk_fma_f32 v[12:13], v[2:3], v[82:83], v[14:15]
	v_mul_f32_e32 v14, v7, v7
	v_mul_f32_e32 v15, v9, v9
	v_mul_f32_e32 v16, v13, v13
	v_mul_f32_e32 v17, v11, v11
	v_cvt_pk_bf16_f32 v2, v6, v7
	v_cvt_pk_bf16_f32 v3, v8, v9
	v_cvt_pk_bf16_f32 v4, v12, v13
	v_cvt_pk_bf16_f32 v5, v10, v11
	v_fmac_f32_e32 v14, v6, v6
	v_fmac_f32_e32 v15, v8, v8
	v_fmac_f32_e32 v16, v12, v12
	v_fmac_f32_e32 v17, v10, v10
	global_store_dwordx4 v[32:33], v[2:5], off offset:256
	v_pk_mul_f32 v[8:9], v[136:137], v[8:9]
	v_pk_mul_f32 v[10:11], v[130:131], v[10:11]
	v_add_f32_e32 v2, v14, v15
	v_add_f32_e32 v3, v16, v17
	v_add_f32_e32 v2, v2, v3
	v_add_f32_e32 v5, v20, v2
	v_mov_b32_e32 v14, v5
	s_nop 1
	v_permlane16_swap_b32_e32 v5, v14
	v_pk_mul_f32 v[2:3], v[134:135], v[6:7]
	v_pk_mul_f32 v[6:7], v[132:133], v[12:13]
	v_cvt_pk_bf16_f32 v4, v2, v3
	v_cvt_pk_bf16_f32 v6, v6, v7
	s_waitcnt lgkmcnt(0)
	v_add_f32_e32 v2, v5, v14
	v_mov_b32_e32 v3, v2
	s_nop 1
	v_permlane32_swap_b32_e32 v2, v3
	v_cvt_pk_bf16_f32 v5, v8, v9
	v_cvt_pk_bf16_f32 v7, v10, v11
	global_store_dwordx4 v[28:29], v[4:7], off offset:256
	s_and_saveexec_b64 s[40:41], s[0:1]
	s_cbranch_execz .LBB0_512
	v_lshlrev_b64 v[4:5], 6, v[18:19]
	v_lshl_add_u64 v[4:5], s[12:13], 0, v[4:5]
	v_lshl_add_u64 v[4:5], s[38:39], 2, v[4:5]
	s_lshl_b32 s8, s72, 2
	v_lshl_add_u64 v[4:5], v[4:5], 0, s[8:9]
	s_waitcnt lgkmcnt(0)
	v_add_f32_e32 v2, v2, v3
	global_store_dword v[4:5], v2, off

.LBB0_668:
	v_lshl_add_u32 v164, s72, 8, v166
	v_ashrrev_i32_e32 v165, 31, v164
	s_ashr_i32 s28, s72, 4
	v_lshl_or_b32 v162, s10, 8, v168
	v_lshlrev_b64 v[82:83], 11, v[164:165]
	s_mul_hi_i32 s29, s28, 0x6000
	s_mulk_i32 s28, 0x6000
	v_ashrrev_i32_e32 v163, 31, v162
	v_lshl_add_u64 v[82:83], s[20:21], 0, v[82:83]
	s_add_u32 s28, s46, s28
	v_lshl_add_u64 v[182:183], v[162:163], 1, v[82:83]
	s_addc_u32 s29, s47, s29
	global_load_dwordx4 v[174:177], v[182:183], off
	global_load_dwordx4 v[178:181], v[182:183], off offset:256
	v_add_co_u32_e32 v252, vcc, 0x8000, v182
	v_addc_co_u32_e32 v253, vcc, 0, v183, vcc
	global_load_dwordx4 v[194:197], v[252:253], off
	global_load_dwordx4 v[198:201], v[252:253], off offset:256
	v_add_co_u32_e32 v252, vcc, 0x10000, v182
	v_addc_co_u32_e32 v253, vcc, 0, v183, vcc
	global_load_dwordx4 v[202:205], v[252:253], off
	global_load_dwordx4 v[206:209], v[252:253], off offset:256
	v_add_co_u32_e32 v252, vcc, 0x18000, v182
	v_addc_co_u32_e32 v253, vcc, 0, v183, vcc
	global_load_dwordx4 v[212:215], v[252:253], off
	global_load_dwordx4 v[216:219], v[252:253], off offset:256
	v_add_co_u32_e32 v252, vcc, 0x40000, v182
	v_addc_co_u32_e32 v253, vcc, 0, v183, vcc
	global_load_dwordx4 v[220:223], v[252:253], off
	global_load_dwordx4 v[224:227], v[252:253], off offset:256
	v_add_co_u32_e32 v252, vcc, 0x48000, v182
	v_addc_co_u32_e32 v253, vcc, 0, v183, vcc
	global_load_dwordx4 v[228:231], v[252:253], off
	global_load_dwordx4 v[232:235], v[252:253], off offset:256
	v_add_co_u32_e32 v252, vcc, 0x50000, v182
	v_addc_co_u32_e32 v253, vcc, 0, v183, vcc
	global_load_dwordx4 v[236:239], v[252:253], off
	global_load_dwordx4 v[240:243], v[252:253], off offset:256
	v_add_co_u32_e32 v252, vcc, 0x58000, v182
	v_addc_co_u32_e32 v253, vcc, 0, v183, vcc
	global_load_dwordx4 v[244:247], v[252:253], off
	global_load_dwordx4 v[248:251], v[252:253], off offset:256
	v_lshl_add_u64 v[82:83], v[162:163], 2, s[28:29]
	global_load_dwordx4 v[94:97], v[82:83], off
	global_load_dwordx4 v[90:93], v[82:83], off offset:16
	global_load_dwordx4 v[86:89], v[82:83], off offset:512
	s_nop 0
	global_load_dwordx4 v[82:85], v[82:83], off offset:528
	v_pk_add_f32 v[184:185], v[132:133], 0 op_sel_hi:[1,0]
	v_and_b32_e32 v133, 64, v172
	v_xor_b32_e32 v132, 16, v172
	v_add_u32_e32 v133, 64, v133
	v_pk_add_f32 v[144:145], v[144:145], 0 op_sel_hi:[1,0]
	v_pk_add_f32 v[142:143], v[142:143], 0 op_sel_hi:[1,0]
	v_pk_add_f32 v[140:141], v[140:141], 0 op_sel_hi:[1,0]
	v_pk_add_f32 v[138:139], v[138:139], 0 op_sel_hi:[1,0]
	v_pk_add_f32 v[136:137], v[136:137], 0 op_sel_hi:[1,0]
	v_pk_add_f32 v[134:135], v[134:135], 0 op_sel_hi:[1,0]
	v_pk_add_f32 v[130:131], v[130:131], 0 op_sel_hi:[1,0]
	v_xor_b32_e32 v173, 32, v172
	v_cmp_lt_i32_e32 vcc, v132, v133
	s_lshl_b32 s28, s10, 2
	s_ashr_i32 s29, s28, 31
	v_cndmask_b32_e32 v132, v172, v132, vcc
	v_cmp_lt_i32_e32 vcc, v173, v133
	v_lshlrev_b32_e32 v132, 2, v132
	s_waitcnt vmcnt(0)
	v_lshlrev_b32_e32 v186, 16, v174
	v_and_b32_e32 v187, 0xffff0000, v174
	v_lshlrev_b32_e32 v174, 16, v175
	v_and_b32_e32 v175, 0xffff0000, v175
	v_lshlrev_b32_e32 v188, 16, v176
	v_and_b32_e32 v189, 0xffff0000, v176
	v_lshlrev_b32_e32 v176, 16, v177
	v_and_b32_e32 v177, 0xffff0000, v177
	v_lshlrev_b32_e32 v190, 16, v178
	v_and_b32_e32 v191, 0xffff0000, v178
	v_lshlrev_b32_e32 v178, 16, v179
	v_and_b32_e32 v179, 0xffff0000, v179
	v_lshlrev_b32_e32 v192, 16, v180
	v_and_b32_e32 v193, 0xffff0000, v180
	v_lshlrev_b32_e32 v180, 16, v181
	v_and_b32_e32 v181, 0xffff0000, v181
	v_pk_fma_f32 v[144:145], v[144:145], v[96:97], v[174:175]
	v_pk_fma_f32 v[142:143], v[142:143], v[94:95], v[186:187]
	v_pk_fma_f32 v[140:141], v[140:141], v[92:93], v[176:177]
	v_pk_fma_f32 v[138:139], v[138:139], v[90:91], v[188:189]
	v_pk_fma_f32 v[174:175], v[136:137], v[88:89], v[178:179]
	v_pk_fma_f32 v[176:177], v[134:135], v[86:87], v[190:191]
	v_pk_fma_f32 v[178:179], v[184:185], v[84:85], v[180:181]
	v_pk_fma_f32 v[180:181], v[130:131], v[82:83], v[192:193]
	v_cndmask_b32_e32 v133, v172, v173, vcc
	v_mul_f32_e32 v130, v143, v143
	v_mul_f32_e32 v131, v145, v145
	v_mul_f32_e32 v136, v139, v139
	v_mul_f32_e32 v137, v141, v141
	v_cvt_pk_bf16_f32 v134, v142, v143
	v_cvt_pk_bf16_f32 v135, v144, v145
	v_mul_f32_e32 v143, v177, v177
	v_mul_f32_e32 v145, v175, v175
	v_mul_f32_e32 v173, v181, v181
	v_mul_f32_e32 v184, v179, v179
	v_fmac_f32_e32 v130, v142, v142
	v_fmac_f32_e32 v131, v144, v144
	v_fmac_f32_e32 v136, v138, v138
	v_fmac_f32_e32 v137, v140, v140
	v_fmac_f32_e32 v143, v176, v176
	v_fmac_f32_e32 v145, v174, v174
	v_fmac_f32_e32 v173, v180, v180
	v_fmac_f32_e32 v184, v178, v178
	v_add_f32_e32 v130, v130, v131
	v_add_f32_e32 v131, v136, v137
	v_add_f32_e32 v136, v143, v145
	v_add_f32_e32 v137, v173, v184
	v_add_f32_e32 v130, v130, v131
	v_add_f32_e32 v131, v136, v137
	v_add_f32_e32 v130, v130, v131
	v_mov_b32_e32 v131, v130
	s_nop 1
	v_permlane16_swap_b32_e32 v130, v131
	v_lshlrev_b32_e32 v133, 2, v133
	v_cvt_pk_bf16_f32 v136, v138, v139
	v_cvt_pk_bf16_f32 v137, v140, v141
	v_cvt_pk_bf16_f32 v138, v176, v177
	s_waitcnt lgkmcnt(0)
	v_add_f32_e32 v130, v130, v131
	v_mov_b32_e32 v131, v130
	s_nop 1
	v_permlane32_swap_b32_e32 v130, v131
	v_cvt_pk_bf16_f32 v139, v174, v175
	v_cvt_pk_bf16_f32 v140, v180, v181
	v_cvt_pk_bf16_f32 v141, v178, v179
	global_store_dwordx4 v[182:183], v[134:137], off
	global_store_dwordx4 v[182:183], v[138:141], off offset:256
	s_and_saveexec_b64 s[30:31], s[0:1]
	s_cbranch_execz .LBB0_670
	v_lshlrev_b64 v[134:135], 6, v[164:165]
	v_lshl_add_u64 v[134:135], s[14:15], 0, v[134:135]
	v_lshl_add_u64 v[134:135], s[28:29], 2, v[134:135]
	s_lshl_b32 s10, s62, 2
	v_lshl_add_u64 v[134:135], v[134:135], 0, s[10:11]
	s_waitcnt lgkmcnt(0)
	v_add_f32_e32 v130, v130, v131
	global_store_dword v[134:135], v130, off
.LBB0_670:
	s_or_b64 exec, exec, s[30:31]
	v_or_b32_e32 v130, 16, v164
	s_waitcnt lgkmcnt(0)
	v_ashrrev_i32_e32 v131, 31, v130
	v_lshlrev_b64 v[134:135], 11, v[130:131]
	v_lshl_add_u64 v[134:135], s[20:21], 0, v[134:135]
	v_lshl_add_u64 v[142:143], v[162:163], 1, v[134:135]
	s_nop 1
	v_pk_mov_b32 v[134:135], v[194:195], v[194:195] op_sel:[0,1]
	v_pk_mov_b32 v[136:137], v[196:197], v[196:197] op_sel:[0,1]
	v_pk_mov_b32 v[138:139], v[198:199], v[198:199] op_sel:[0,1]
	v_pk_mov_b32 v[140:141], v[200:201], v[200:201] op_sel:[0,1]
	v_pk_add_f32 v[128:129], v[128:129], 0 op_sel_hi:[1,0]
	v_pk_add_f32 v[126:127], v[126:127], 0 op_sel_hi:[1,0]
	v_pk_add_f32 v[124:125], v[124:125], 0 op_sel_hi:[1,0]
	v_pk_add_f32 v[122:123], v[122:123], 0 op_sel_hi:[1,0]
	v_pk_add_f32 v[120:121], v[120:121], 0 op_sel_hi:[1,0]
	v_pk_add_f32 v[118:119], v[118:119], 0 op_sel_hi:[1,0]
	v_pk_add_f32 v[116:117], v[116:117], 0 op_sel_hi:[1,0]
	v_pk_add_f32 v[114:115], v[114:115], 0 op_sel_hi:[1,0]
	v_lshlrev_b32_e32 v144, 16, v134
	v_and_b32_e32 v145, 0xffff0000, v134
	v_lshlrev_b32_e32 v134, 16, v135
	v_and_b32_e32 v135, 0xffff0000, v135
	v_lshlrev_b32_e32 v174, 16, v136
	v_and_b32_e32 v175, 0xffff0000, v136
	v_lshlrev_b32_e32 v136, 16, v137
	v_and_b32_e32 v137, 0xffff0000, v137
	v_lshlrev_b32_e32 v176, 16, v138
	v_and_b32_e32 v177, 0xffff0000, v138
	v_lshlrev_b32_e32 v138, 16, v139
	v_and_b32_e32 v139, 0xffff0000, v139
	v_lshlrev_b32_e32 v178, 16, v140
	v_and_b32_e32 v179, 0xffff0000, v140
	v_lshlrev_b32_e32 v140, 16, v141
	v_and_b32_e32 v141, 0xffff0000, v141
	v_pk_fma_f32 v[128:129], v[128:129], v[96:97], v[134:135]
	v_pk_fma_f32 v[126:127], v[126:127], v[94:95], v[144:145]
	v_pk_fma_f32 v[124:125], v[124:125], v[92:93], v[136:137]
	v_pk_fma_f32 v[122:123], v[122:123], v[90:91], v[174:175]
	v_pk_fma_f32 v[120:121], v[120:121], v[88:89], v[138:139]
	v_pk_fma_f32 v[118:119], v[118:119], v[86:87], v[176:177]
	v_pk_fma_f32 v[134:135], v[116:117], v[84:85], v[140:141]
	v_pk_fma_f32 v[136:137], v[114:115], v[82:83], v[178:179]
	v_mul_f32_e32 v116, v127, v127
	v_mul_f32_e32 v117, v129, v129
	v_mul_f32_e32 v138, v123, v123
	v_mul_f32_e32 v139, v125, v125
	v_cvt_pk_bf16_f32 v114, v126, v127
	v_cvt_pk_bf16_f32 v115, v128, v129
	v_mul_f32_e32 v127, v119, v119
	v_mul_f32_e32 v129, v121, v121
	v_mul_f32_e32 v140, v137, v137
	v_mul_f32_e32 v141, v135, v135
	v_fmac_f32_e32 v116, v126, v126
	v_fmac_f32_e32 v117, v128, v128
	v_fmac_f32_e32 v138, v122, v122
	v_fmac_f32_e32 v139, v124, v124
	v_fmac_f32_e32 v127, v118, v118
	v_fmac_f32_e32 v129, v120, v120
	v_fmac_f32_e32 v140, v136, v136
	v_fmac_f32_e32 v141, v134, v134
	v_add_f32_e32 v116, v116, v117
	v_add_f32_e32 v117, v138, v139
	v_add_f32_e32 v126, v127, v129
	v_add_f32_e32 v127, v140, v141
	v_add_f32_e32 v116, v116, v117
	v_add_f32_e32 v117, v126, v127
	v_add_f32_e32 v126, v116, v117
	v_mov_b32_e32 v127, v126
	s_nop 1
	v_permlane16_swap_b32_e32 v126, v127
	v_cvt_pk_bf16_f32 v116, v122, v123
	v_cvt_pk_bf16_f32 v117, v124, v125
	global_store_dwordx4 v[142:143], v[114:117], off
	s_waitcnt lgkmcnt(0)
	s_nop 0
	v_add_f32_e32 v114, v126, v127
	v_mov_b32_e32 v115, v114
	s_nop 1
	v_permlane32_swap_b32_e32 v114, v115
	v_cvt_pk_bf16_f32 v116, v118, v119
	v_cvt_pk_bf16_f32 v117, v120, v121
	v_cvt_pk_bf16_f32 v118, v136, v137
	v_cvt_pk_bf16_f32 v119, v134, v135
	global_store_dwordx4 v[142:143], v[116:119], off offset:256
	s_and_saveexec_b64 s[30:31], s[0:1]
	s_cbranch_execz .LBB0_672
	v_lshlrev_b64 v[116:117], 6, v[130:131]
	v_lshl_add_u64 v[116:117], s[14:15], 0, v[116:117]
	v_lshl_add_u64 v[116:117], s[28:29], 2, v[116:117]
	s_lshl_b32 s10, s62, 2
	v_lshl_add_u64 v[116:117], v[116:117], 0, s[10:11]
	s_waitcnt lgkmcnt(0)
	v_add_f32_e32 v114, v114, v115
	global_store_dword v[116:117], v114, off
.LBB0_672:
	s_or_b64 exec, exec, s[30:31]
	v_or_b32_e32 v114, 32, v164
	s_waitcnt lgkmcnt(0)
	v_ashrrev_i32_e32 v115, 31, v114
	v_lshlrev_b64 v[116:117], 11, v[114:115]
	v_lshl_add_u64 v[116:117], s[20:21], 0, v[116:117]
	v_lshl_add_u64 v[124:125], v[162:163], 1, v[116:117]
	s_nop 1
	v_pk_mov_b32 v[116:117], v[202:203], v[202:203] op_sel:[0,1]
	v_pk_mov_b32 v[118:119], v[204:205], v[204:205] op_sel:[0,1]
	v_pk_mov_b32 v[120:121], v[206:207], v[206:207] op_sel:[0,1]
	v_pk_mov_b32 v[122:123], v[208:209], v[208:209] op_sel:[0,1]
	v_pk_add_f32 v[112:113], v[112:113], 0 op_sel_hi:[1,0]
	v_pk_add_f32 v[110:111], v[110:111], 0 op_sel_hi:[1,0]
	v_pk_add_f32 v[108:109], v[108:109], 0 op_sel_hi:[1,0]
	v_pk_add_f32 v[106:107], v[106:107], 0 op_sel_hi:[1,0]
	v_pk_add_f32 v[104:105], v[104:105], 0 op_sel_hi:[1,0]
	v_pk_add_f32 v[102:103], v[102:103], 0 op_sel_hi:[1,0]
	v_pk_add_f32 v[100:101], v[100:101], 0 op_sel_hi:[1,0]
	v_pk_add_f32 v[98:99], v[98:99], 0 op_sel_hi:[1,0]
	v_lshlrev_b32_e32 v126, 16, v116
	v_and_b32_e32 v127, 0xffff0000, v116
	v_lshlrev_b32_e32 v116, 16, v117
	v_and_b32_e32 v117, 0xffff0000, v117
	v_lshlrev_b32_e32 v128, 16, v118
	v_and_b32_e32 v129, 0xffff0000, v118
	v_lshlrev_b32_e32 v118, 16, v119
	v_and_b32_e32 v119, 0xffff0000, v119
	v_lshlrev_b32_e32 v130, 16, v120
	v_and_b32_e32 v131, 0xffff0000, v120
	v_lshlrev_b32_e32 v120, 16, v121
	v_and_b32_e32 v121, 0xffff0000, v121
	v_lshlrev_b32_e32 v134, 16, v122
	v_and_b32_e32 v135, 0xffff0000, v122
	v_lshlrev_b32_e32 v122, 16, v123
	v_and_b32_e32 v123, 0xffff0000, v123
	v_pk_fma_f32 v[112:113], v[112:113], v[96:97], v[116:117]
	v_pk_fma_f32 v[110:111], v[110:111], v[94:95], v[126:127]
	v_pk_fma_f32 v[108:109], v[108:109], v[92:93], v[118:119]
	v_pk_fma_f32 v[106:107], v[106:107], v[90:91], v[128:129]
	v_pk_fma_f32 v[104:105], v[104:105], v[88:89], v[120:121]
	v_pk_fma_f32 v[102:103], v[102:103], v[86:87], v[130:131]
	v_pk_fma_f32 v[116:117], v[100:101], v[84:85], v[122:123]
	v_pk_fma_f32 v[118:119], v[98:99], v[82:83], v[134:135]
	v_mul_f32_e32 v100, v111, v111
	v_mul_f32_e32 v101, v113, v113
	v_mul_f32_e32 v120, v107, v107
	v_mul_f32_e32 v121, v109, v109
	v_cvt_pk_bf16_f32 v98, v110, v111
	v_cvt_pk_bf16_f32 v99, v112, v113
	v_mul_f32_e32 v111, v103, v103
	v_mul_f32_e32 v113, v105, v105
	v_mul_f32_e32 v122, v119, v119
	v_mul_f32_e32 v123, v117, v117
	v_fmac_f32_e32 v100, v110, v110
	v_fmac_f32_e32 v101, v112, v112
	v_fmac_f32_e32 v120, v106, v106
	v_fmac_f32_e32 v121, v108, v108
	v_fmac_f32_e32 v111, v102, v102
	v_fmac_f32_e32 v113, v104, v104
	v_fmac_f32_e32 v122, v118, v118
	v_fmac_f32_e32 v123, v116, v116
	v_add_f32_e32 v100, v100, v101
	v_add_f32_e32 v101, v120, v121
	v_add_f32_e32 v110, v111, v113
	v_add_f32_e32 v111, v122, v123
	v_add_f32_e32 v100, v100, v101
	v_add_f32_e32 v101, v110, v111
	v_add_f32_e32 v110, v100, v101
	v_mov_b32_e32 v111, v110
	s_nop 1
	v_permlane16_swap_b32_e32 v110, v111
	v_cvt_pk_bf16_f32 v100, v106, v107
	v_cvt_pk_bf16_f32 v101, v108, v109
	global_store_dwordx4 v[124:125], v[98:101], off
	s_waitcnt lgkmcnt(0)
	s_nop 0
	v_add_f32_e32 v98, v110, v111
	v_mov_b32_e32 v99, v98
	s_nop 1
	v_permlane32_swap_b32_e32 v98, v99
	v_cvt_pk_bf16_f32 v100, v102, v103
	v_cvt_pk_bf16_f32 v101, v104, v105
	v_cvt_pk_bf16_f32 v102, v118, v119
	v_cvt_pk_bf16_f32 v103, v116, v117
	global_store_dwordx4 v[124:125], v[100:103], off offset:256
	s_and_saveexec_b64 s[30:31], s[0:1]
	s_cbranch_execz .LBB0_674
	v_lshlrev_b64 v[100:101], 6, v[114:115]
	v_lshl_add_u64 v[100:101], s[14:15], 0, v[100:101]
	v_lshl_add_u64 v[100:101], s[28:29], 2, v[100:101]
	s_lshl_b32 s10, s62, 2
	v_lshl_add_u64 v[100:101], v[100:101], 0, s[10:11]
	s_waitcnt lgkmcnt(0)
	v_add_f32_e32 v98, v98, v99
	global_store_dword v[100:101], v98, off
.LBB0_674:
	s_or_b64 exec, exec, s[30:31]
	v_or_b32_e32 v98, 48, v164
	s_waitcnt lgkmcnt(0)
	v_ashrrev_i32_e32 v99, 31, v98
	v_lshlrev_b64 v[100:101], 11, v[98:99]
	v_lshl_add_u64 v[100:101], s[20:21], 0, v[100:101]
	v_lshl_add_u64 v[108:109], v[162:163], 1, v[100:101]
	s_nop 1
	v_pk_mov_b32 v[100:101], v[212:213], v[212:213] op_sel:[0,1]
	v_pk_mov_b32 v[102:103], v[214:215], v[214:215] op_sel:[0,1]
	v_pk_mov_b32 v[104:105], v[216:217], v[216:217] op_sel:[0,1]
	v_pk_mov_b32 v[106:107], v[218:219], v[218:219] op_sel:[0,1]
	v_pk_add_f32 v[80:81], v[80:81], 0 op_sel_hi:[1,0]
	v_pk_add_f32 v[78:79], v[78:79], 0 op_sel_hi:[1,0]
	v_pk_add_f32 v[76:77], v[76:77], 0 op_sel_hi:[1,0]
	v_pk_add_f32 v[74:75], v[74:75], 0 op_sel_hi:[1,0]
	v_pk_add_f32 v[72:73], v[72:73], 0 op_sel_hi:[1,0]
	v_pk_add_f32 v[70:71], v[70:71], 0 op_sel_hi:[1,0]
	v_pk_add_f32 v[68:69], v[68:69], 0 op_sel_hi:[1,0]
	v_pk_add_f32 v[66:67], v[66:67], 0 op_sel_hi:[1,0]
	v_lshlrev_b32_e32 v110, 16, v100
	v_and_b32_e32 v111, 0xffff0000, v100
	v_lshlrev_b32_e32 v100, 16, v101
	v_and_b32_e32 v101, 0xffff0000, v101
	v_lshlrev_b32_e32 v112, 16, v102
	v_and_b32_e32 v113, 0xffff0000, v102
	v_lshlrev_b32_e32 v102, 16, v103
	v_and_b32_e32 v103, 0xffff0000, v103
	v_lshlrev_b32_e32 v114, 16, v104
	v_and_b32_e32 v115, 0xffff0000, v104
	v_lshlrev_b32_e32 v104, 16, v105
	v_and_b32_e32 v105, 0xffff0000, v105
	v_lshlrev_b32_e32 v116, 16, v106
	v_and_b32_e32 v117, 0xffff0000, v106
	v_lshlrev_b32_e32 v106, 16, v107
	v_and_b32_e32 v107, 0xffff0000, v107
	v_pk_fma_f32 v[80:81], v[80:81], v[96:97], v[100:101]
	v_pk_fma_f32 v[78:79], v[78:79], v[94:95], v[110:111]
	v_pk_fma_f32 v[76:77], v[76:77], v[92:93], v[102:103]
	v_pk_fma_f32 v[74:75], v[74:75], v[90:91], v[112:113]
	v_pk_fma_f32 v[72:73], v[72:73], v[88:89], v[104:105]
	v_pk_fma_f32 v[70:71], v[70:71], v[86:87], v[114:115]
	v_pk_fma_f32 v[100:101], v[68:69], v[84:85], v[106:107]
	v_pk_fma_f32 v[102:103], v[66:67], v[82:83], v[116:117]
	v_mul_f32_e32 v68, v79, v79
	v_mul_f32_e32 v69, v81, v81
	v_mul_f32_e32 v104, v75, v75
	v_mul_f32_e32 v105, v77, v77
	v_cvt_pk_bf16_f32 v66, v78, v79
	v_cvt_pk_bf16_f32 v67, v80, v81
	v_mul_f32_e32 v79, v71, v71
	v_mul_f32_e32 v81, v73, v73
	v_mul_f32_e32 v106, v103, v103
	v_mul_f32_e32 v107, v101, v101
	v_fmac_f32_e32 v68, v78, v78
	v_fmac_f32_e32 v69, v80, v80
	v_fmac_f32_e32 v104, v74, v74
	v_fmac_f32_e32 v105, v76, v76
	v_fmac_f32_e32 v79, v70, v70
	v_fmac_f32_e32 v81, v72, v72
	v_fmac_f32_e32 v106, v102, v102
	v_fmac_f32_e32 v107, v100, v100
	v_add_f32_e32 v68, v68, v69
	v_add_f32_e32 v69, v104, v105
	v_add_f32_e32 v78, v79, v81
	v_add_f32_e32 v79, v106, v107
	v_add_f32_e32 v68, v68, v69
	v_add_f32_e32 v69, v78, v79
	v_add_f32_e32 v78, v68, v69
	v_mov_b32_e32 v79, v78
	s_nop 1
	v_permlane16_swap_b32_e32 v78, v79
	v_cvt_pk_bf16_f32 v68, v74, v75
	v_cvt_pk_bf16_f32 v69, v76, v77
	global_store_dwordx4 v[108:109], v[66:69], off
	s_waitcnt lgkmcnt(0)
	s_nop 0
	v_add_f32_e32 v66, v78, v79
	v_mov_b32_e32 v67, v66
	s_nop 1
	v_permlane32_swap_b32_e32 v66, v67
	v_cvt_pk_bf16_f32 v68, v70, v71
	v_cvt_pk_bf16_f32 v69, v72, v73
	v_cvt_pk_bf16_f32 v70, v102, v103
	v_cvt_pk_bf16_f32 v71, v100, v101
	global_store_dwordx4 v[108:109], v[68:71], off offset:256
	s_and_saveexec_b64 s[30:31], s[0:1]
	s_cbranch_execz .LBB0_676
	v_lshlrev_b64 v[68:69], 6, v[98:99]
	v_lshl_add_u64 v[68:69], s[14:15], 0, v[68:69]
	v_lshl_add_u64 v[68:69], s[28:29], 2, v[68:69]
	s_lshl_b32 s10, s62, 2
	v_lshl_add_u64 v[68:69], v[68:69], 0, s[10:11]
	s_waitcnt lgkmcnt(0)
	v_add_f32_e32 v66, v66, v67
	global_store_dword v[68:69], v66, off
.LBB0_676:
	s_or_b64 exec, exec, s[30:31]
	v_add_u32_e32 v66, 0x80, v164
	s_waitcnt lgkmcnt(0)
	v_ashrrev_i32_e32 v67, 31, v66
	v_lshlrev_b64 v[68:69], 11, v[66:67]
	v_lshl_add_u64 v[68:69], s[20:21], 0, v[68:69]
	v_lshl_add_u64 v[76:77], v[162:163], 1, v[68:69]
	s_nop 1
	v_pk_mov_b32 v[68:69], v[220:221], v[220:221] op_sel:[0,1]
	v_pk_mov_b32 v[70:71], v[222:223], v[222:223] op_sel:[0,1]
	v_pk_mov_b32 v[72:73], v[224:225], v[224:225] op_sel:[0,1]
	v_pk_mov_b32 v[74:75], v[226:227], v[226:227] op_sel:[0,1]
	v_pk_add_f32 v[64:65], v[64:65], 0 op_sel_hi:[1,0]
	v_pk_add_f32 v[62:63], v[62:63], 0 op_sel_hi:[1,0]
	v_pk_add_f32 v[60:61], v[60:61], 0 op_sel_hi:[1,0]
	v_pk_add_f32 v[58:59], v[58:59], 0 op_sel_hi:[1,0]
	v_pk_add_f32 v[56:57], v[56:57], 0 op_sel_hi:[1,0]
	v_pk_add_f32 v[54:55], v[54:55], 0 op_sel_hi:[1,0]
	v_pk_add_f32 v[52:53], v[52:53], 0 op_sel_hi:[1,0]
	v_pk_add_f32 v[50:51], v[50:51], 0 op_sel_hi:[1,0]
	v_lshlrev_b32_e32 v78, 16, v68
	v_and_b32_e32 v79, 0xffff0000, v68
	v_lshlrev_b32_e32 v68, 16, v69
	v_and_b32_e32 v69, 0xffff0000, v69
	v_lshlrev_b32_e32 v80, 16, v70
	v_and_b32_e32 v81, 0xffff0000, v70
	v_lshlrev_b32_e32 v70, 16, v71
	v_and_b32_e32 v71, 0xffff0000, v71
	v_lshlrev_b32_e32 v98, 16, v72
	v_and_b32_e32 v99, 0xffff0000, v72
	v_lshlrev_b32_e32 v72, 16, v73
	v_and_b32_e32 v73, 0xffff0000, v73
	v_lshlrev_b32_e32 v100, 16, v74
	v_and_b32_e32 v101, 0xffff0000, v74
	v_lshlrev_b32_e32 v74, 16, v75
	v_and_b32_e32 v75, 0xffff0000, v75
	v_pk_fma_f32 v[64:65], v[64:65], v[96:97], v[68:69]
	v_pk_fma_f32 v[62:63], v[62:63], v[94:95], v[78:79]
	v_pk_fma_f32 v[60:61], v[60:61], v[92:93], v[70:71]
	v_pk_fma_f32 v[58:59], v[58:59], v[90:91], v[80:81]
	v_pk_fma_f32 v[56:57], v[56:57], v[88:89], v[72:73]
	v_pk_fma_f32 v[54:55], v[54:55], v[86:87], v[98:99]
	v_pk_fma_f32 v[68:69], v[52:53], v[84:85], v[74:75]
	v_pk_fma_f32 v[70:71], v[50:51], v[82:83], v[100:101]
	v_mul_f32_e32 v52, v63, v63
	v_mul_f32_e32 v53, v65, v65
	v_mul_f32_e32 v72, v59, v59
	v_mul_f32_e32 v73, v61, v61
	v_cvt_pk_bf16_f32 v50, v62, v63
	v_cvt_pk_bf16_f32 v51, v64, v65
	v_mul_f32_e32 v63, v55, v55
	v_mul_f32_e32 v65, v57, v57
	v_mul_f32_e32 v74, v71, v71
	v_mul_f32_e32 v75, v69, v69
	v_fmac_f32_e32 v52, v62, v62
	v_fmac_f32_e32 v53, v64, v64
	v_fmac_f32_e32 v72, v58, v58
	v_fmac_f32_e32 v73, v60, v60
	v_fmac_f32_e32 v63, v54, v54
	v_fmac_f32_e32 v65, v56, v56
	v_fmac_f32_e32 v74, v70, v70
	v_fmac_f32_e32 v75, v68, v68
	v_add_f32_e32 v52, v52, v53
	v_add_f32_e32 v53, v72, v73
	v_add_f32_e32 v62, v63, v65
	v_add_f32_e32 v63, v74, v75
	v_add_f32_e32 v52, v52, v53
	v_add_f32_e32 v53, v62, v63
	v_add_f32_e32 v62, v52, v53
	v_mov_b32_e32 v63, v62
	s_nop 1
	v_permlane16_swap_b32_e32 v62, v63
	v_cvt_pk_bf16_f32 v52, v58, v59
	v_cvt_pk_bf16_f32 v53, v60, v61
	global_store_dwordx4 v[76:77], v[50:53], off
	s_waitcnt lgkmcnt(0)
	s_nop 0
	v_add_f32_e32 v50, v62, v63
	v_mov_b32_e32 v51, v50
	s_nop 1
	v_permlane32_swap_b32_e32 v50, v51
	v_cvt_pk_bf16_f32 v52, v54, v55
	v_cvt_pk_bf16_f32 v53, v56, v57
	v_cvt_pk_bf16_f32 v54, v70, v71
	v_cvt_pk_bf16_f32 v55, v68, v69
	global_store_dwordx4 v[76:77], v[52:55], off offset:256
	s_and_saveexec_b64 s[30:31], s[0:1]
	s_cbranch_execz .LBB0_678
	v_lshlrev_b64 v[52:53], 6, v[66:67]
	v_lshl_add_u64 v[52:53], s[14:15], 0, v[52:53]
	v_lshl_add_u64 v[52:53], s[28:29], 2, v[52:53]
	s_lshl_b32 s10, s62, 2
	v_lshl_add_u64 v[52:53], v[52:53], 0, s[10:11]
	s_waitcnt lgkmcnt(0)
	v_add_f32_e32 v50, v50, v51
	global_store_dword v[52:53], v50, off
.LBB0_678:
	s_or_b64 exec, exec, s[30:31]
	v_add_u32_e32 v50, 0x90, v164
	s_waitcnt lgkmcnt(0)
	v_ashrrev_i32_e32 v51, 31, v50
	v_lshlrev_b64 v[52:53], 11, v[50:51]
	v_lshl_add_u64 v[52:53], s[20:21], 0, v[52:53]
	v_lshl_add_u64 v[60:61], v[162:163], 1, v[52:53]
	s_nop 1
	v_pk_mov_b32 v[52:53], v[228:229], v[228:229] op_sel:[0,1]
	v_pk_mov_b32 v[54:55], v[230:231], v[230:231] op_sel:[0,1]
	v_pk_mov_b32 v[56:57], v[232:233], v[232:233] op_sel:[0,1]
	v_pk_mov_b32 v[58:59], v[234:235], v[234:235] op_sel:[0,1]
	v_pk_add_f32 v[48:49], v[48:49], 0 op_sel_hi:[1,0]
	v_pk_add_f32 v[46:47], v[46:47], 0 op_sel_hi:[1,0]
	v_pk_add_f32 v[44:45], v[44:45], 0 op_sel_hi:[1,0]
	v_pk_add_f32 v[42:43], v[42:43], 0 op_sel_hi:[1,0]
	v_pk_add_f32 v[40:41], v[40:41], 0 op_sel_hi:[1,0]
	v_pk_add_f32 v[38:39], v[38:39], 0 op_sel_hi:[1,0]
	v_pk_add_f32 v[36:37], v[36:37], 0 op_sel_hi:[1,0]
	v_pk_add_f32 v[34:35], v[34:35], 0 op_sel_hi:[1,0]
	v_lshlrev_b32_e32 v62, 16, v52
	v_and_b32_e32 v63, 0xffff0000, v52
	v_lshlrev_b32_e32 v52, 16, v53
	v_and_b32_e32 v53, 0xffff0000, v53
	v_lshlrev_b32_e32 v64, 16, v54
	v_and_b32_e32 v65, 0xffff0000, v54
	v_lshlrev_b32_e32 v54, 16, v55
	v_and_b32_e32 v55, 0xffff0000, v55
	v_lshlrev_b32_e32 v66, 16, v56
	v_and_b32_e32 v67, 0xffff0000, v56
	v_lshlrev_b32_e32 v56, 16, v57
	v_and_b32_e32 v57, 0xffff0000, v57
	v_lshlrev_b32_e32 v68, 16, v58
	v_and_b32_e32 v69, 0xffff0000, v58
	v_lshlrev_b32_e32 v58, 16, v59
	v_and_b32_e32 v59, 0xffff0000, v59
	v_pk_fma_f32 v[48:49], v[48:49], v[96:97], v[52:53]
	v_pk_fma_f32 v[46:47], v[46:47], v[94:95], v[62:63]
	v_pk_fma_f32 v[44:45], v[44:45], v[92:93], v[54:55]
	v_pk_fma_f32 v[42:43], v[42:43], v[90:91], v[64:65]
	v_pk_fma_f32 v[40:41], v[40:41], v[88:89], v[56:57]
	v_pk_fma_f32 v[38:39], v[38:39], v[86:87], v[66:67]
	v_pk_fma_f32 v[52:53], v[36:37], v[84:85], v[58:59]
	v_pk_fma_f32 v[54:55], v[34:35], v[82:83], v[68:69]
	v_mul_f32_e32 v36, v47, v47
	v_mul_f32_e32 v37, v49, v49
	v_mul_f32_e32 v56, v43, v43
	v_mul_f32_e32 v57, v45, v45
	v_cvt_pk_bf16_f32 v34, v46, v47
	v_cvt_pk_bf16_f32 v35, v48, v49
	v_mul_f32_e32 v47, v39, v39
	v_mul_f32_e32 v49, v41, v41
	v_mul_f32_e32 v58, v55, v55
	v_mul_f32_e32 v59, v53, v53
	v_fmac_f32_e32 v36, v46, v46
	v_fmac_f32_e32 v37, v48, v48
	v_fmac_f32_e32 v56, v42, v42
	v_fmac_f32_e32 v57, v44, v44
	v_fmac_f32_e32 v47, v38, v38
	v_fmac_f32_e32 v49, v40, v40
	v_fmac_f32_e32 v58, v54, v54
	v_fmac_f32_e32 v59, v52, v52
	v_add_f32_e32 v36, v36, v37
	v_add_f32_e32 v37, v56, v57
	v_add_f32_e32 v46, v47, v49
	v_add_f32_e32 v47, v58, v59
	v_add_f32_e32 v36, v36, v37
	v_add_f32_e32 v37, v46, v47
	v_add_f32_e32 v46, v36, v37
	v_mov_b32_e32 v47, v46
	s_nop 1
	v_permlane16_swap_b32_e32 v46, v47
	v_cvt_pk_bf16_f32 v36, v42, v43
	v_cvt_pk_bf16_f32 v37, v44, v45
	global_store_dwordx4 v[60:61], v[34:37], off
	s_waitcnt lgkmcnt(0)
	s_nop 0
	v_add_f32_e32 v34, v46, v47
	v_mov_b32_e32 v35, v34
	s_nop 1
	v_permlane32_swap_b32_e32 v34, v35
	v_cvt_pk_bf16_f32 v36, v38, v39
	v_cvt_pk_bf16_f32 v37, v40, v41
	v_cvt_pk_bf16_f32 v38, v54, v55
	v_cvt_pk_bf16_f32 v39, v52, v53
	global_store_dwordx4 v[60:61], v[36:39], off offset:256
	s_and_saveexec_b64 s[30:31], s[0:1]
	s_cbranch_execz .LBB0_680
	v_lshlrev_b64 v[36:37], 6, v[50:51]
	v_lshl_add_u64 v[36:37], s[14:15], 0, v[36:37]
	v_lshl_add_u64 v[36:37], s[28:29], 2, v[36:37]
	s_lshl_b32 s10, s62, 2
	v_lshl_add_u64 v[36:37], v[36:37], 0, s[10:11]
	s_waitcnt lgkmcnt(0)
	v_add_f32_e32 v34, v34, v35
	global_store_dword v[36:37], v34, off
.LBB0_680:
	s_or_b64 exec, exec, s[30:31]
	v_add_u32_e32 v34, 0xa0, v164
	s_waitcnt lgkmcnt(0)
	v_ashrrev_i32_e32 v35, 31, v34
	v_lshlrev_b64 v[36:37], 11, v[34:35]
	v_lshl_add_u64 v[36:37], s[20:21], 0, v[36:37]
	v_lshl_add_u64 v[44:45], v[162:163], 1, v[36:37]
	s_nop 1
	v_pk_mov_b32 v[36:37], v[236:237], v[236:237] op_sel:[0,1]
	v_pk_mov_b32 v[38:39], v[238:239], v[238:239] op_sel:[0,1]
	v_pk_mov_b32 v[40:41], v[240:241], v[240:241] op_sel:[0,1]
	v_pk_mov_b32 v[42:43], v[242:243], v[242:243] op_sel:[0,1]
	v_pk_add_f32 v[32:33], v[32:33], 0 op_sel_hi:[1,0]
	v_pk_add_f32 v[30:31], v[30:31], 0 op_sel_hi:[1,0]
	v_pk_add_f32 v[28:29], v[28:29], 0 op_sel_hi:[1,0]
	v_pk_add_f32 v[26:27], v[26:27], 0 op_sel_hi:[1,0]
	v_pk_add_f32 v[24:25], v[24:25], 0 op_sel_hi:[1,0]
	v_pk_add_f32 v[22:23], v[22:23], 0 op_sel_hi:[1,0]
	v_pk_add_f32 v[20:21], v[20:21], 0 op_sel_hi:[1,0]
	v_pk_add_f32 v[18:19], v[18:19], 0 op_sel_hi:[1,0]
	v_lshlrev_b32_e32 v46, 16, v36
	v_and_b32_e32 v47, 0xffff0000, v36
	v_lshlrev_b32_e32 v36, 16, v37
	v_and_b32_e32 v37, 0xffff0000, v37
	v_lshlrev_b32_e32 v48, 16, v38
	v_and_b32_e32 v49, 0xffff0000, v38
	v_lshlrev_b32_e32 v38, 16, v39
	v_and_b32_e32 v39, 0xffff0000, v39
	v_lshlrev_b32_e32 v50, 16, v40
	v_and_b32_e32 v51, 0xffff0000, v40
	v_lshlrev_b32_e32 v40, 16, v41
	v_and_b32_e32 v41, 0xffff0000, v41
	v_lshlrev_b32_e32 v52, 16, v42
	v_and_b32_e32 v53, 0xffff0000, v42
	v_lshlrev_b32_e32 v42, 16, v43
	v_and_b32_e32 v43, 0xffff0000, v43
	v_pk_fma_f32 v[32:33], v[32:33], v[96:97], v[36:37]
	v_pk_fma_f32 v[30:31], v[30:31], v[94:95], v[46:47]
	v_pk_fma_f32 v[28:29], v[28:29], v[92:93], v[38:39]
	v_pk_fma_f32 v[26:27], v[26:27], v[90:91], v[48:49]
	v_pk_fma_f32 v[24:25], v[24:25], v[88:89], v[40:41]
	v_pk_fma_f32 v[22:23], v[22:23], v[86:87], v[50:51]
	v_pk_fma_f32 v[36:37], v[20:21], v[84:85], v[42:43]
	v_pk_fma_f32 v[38:39], v[18:19], v[82:83], v[52:53]
	v_mul_f32_e32 v20, v31, v31
	v_mul_f32_e32 v21, v33, v33
	v_mul_f32_e32 v40, v27, v27
	v_mul_f32_e32 v41, v29, v29
	v_cvt_pk_bf16_f32 v18, v30, v31
	v_cvt_pk_bf16_f32 v19, v32, v33
	v_mul_f32_e32 v31, v23, v23
	v_mul_f32_e32 v33, v25, v25
	v_mul_f32_e32 v42, v39, v39
	v_mul_f32_e32 v43, v37, v37
	v_fmac_f32_e32 v20, v30, v30
	v_fmac_f32_e32 v21, v32, v32
	v_fmac_f32_e32 v40, v26, v26
	v_fmac_f32_e32 v41, v28, v28
	v_fmac_f32_e32 v31, v22, v22
	v_fmac_f32_e32 v33, v24, v24
	v_fmac_f32_e32 v42, v38, v38
	v_fmac_f32_e32 v43, v36, v36
	v_add_f32_e32 v20, v20, v21
	v_add_f32_e32 v21, v40, v41
	v_add_f32_e32 v30, v31, v33
	v_add_f32_e32 v31, v42, v43
	v_add_f32_e32 v20, v20, v21
	v_add_f32_e32 v21, v30, v31
	v_add_f32_e32 v30, v20, v21
	v_mov_b32_e32 v31, v30
	s_nop 1
	v_permlane16_swap_b32_e32 v30, v31
	v_cvt_pk_bf16_f32 v20, v26, v27
	v_cvt_pk_bf16_f32 v21, v28, v29
	global_store_dwordx4 v[44:45], v[18:21], off
	s_waitcnt lgkmcnt(0)
	s_nop 0
	v_add_f32_e32 v18, v30, v31
	v_mov_b32_e32 v19, v18
	s_nop 1
	v_permlane32_swap_b32_e32 v18, v19
	v_cvt_pk_bf16_f32 v20, v22, v23
	v_cvt_pk_bf16_f32 v21, v24, v25
	v_cvt_pk_bf16_f32 v22, v38, v39
	v_cvt_pk_bf16_f32 v23, v36, v37
	global_store_dwordx4 v[44:45], v[20:23], off offset:256
	s_and_saveexec_b64 s[30:31], s[0:1]
	s_cbranch_execz .LBB0_682
	v_lshlrev_b64 v[20:21], 6, v[34:35]
	v_lshl_add_u64 v[20:21], s[14:15], 0, v[20:21]
	v_lshl_add_u64 v[20:21], s[28:29], 2, v[20:21]
	s_lshl_b32 s10, s62, 2
	v_lshl_add_u64 v[20:21], v[20:21], 0, s[10:11]
	s_waitcnt lgkmcnt(0)
	v_add_f32_e32 v18, v18, v19
	global_store_dword v[20:21], v18, off
.LBB0_682:
	s_or_b64 exec, exec, s[30:31]
	v_add_u32_e32 v18, 0xb0, v164
	s_waitcnt lgkmcnt(0)
	v_ashrrev_i32_e32 v19, 31, v18
	v_lshlrev_b64 v[20:21], 11, v[18:19]
	v_lshl_add_u64 v[20:21], s[20:21], 0, v[20:21]
	v_lshl_add_u64 v[28:29], v[162:163], 1, v[20:21]
	s_nop 1
	v_pk_mov_b32 v[20:21], v[244:245], v[244:245] op_sel:[0,1]
	v_pk_mov_b32 v[22:23], v[246:247], v[246:247] op_sel:[0,1]
	v_pk_mov_b32 v[24:25], v[248:249], v[248:249] op_sel:[0,1]
	v_pk_mov_b32 v[26:27], v[250:251], v[250:251] op_sel:[0,1]
	v_pk_add_f32 v[16:17], v[16:17], 0 op_sel_hi:[1,0]
	v_pk_add_f32 v[14:15], v[14:15], 0 op_sel_hi:[1,0]
	v_pk_add_f32 v[12:13], v[12:13], 0 op_sel_hi:[1,0]
	v_pk_add_f32 v[10:11], v[10:11], 0 op_sel_hi:[1,0]
	v_pk_add_f32 v[8:9], v[8:9], 0 op_sel_hi:[1,0]
	v_pk_add_f32 v[6:7], v[6:7], 0 op_sel_hi:[1,0]
	v_pk_add_f32 v[4:5], v[4:5], 0 op_sel_hi:[1,0]
	v_pk_add_f32 v[2:3], v[2:3], 0 op_sel_hi:[1,0]
	v_lshlrev_b32_e32 v30, 16, v20
	v_and_b32_e32 v31, 0xffff0000, v20
	v_lshlrev_b32_e32 v20, 16, v21
	v_and_b32_e32 v21, 0xffff0000, v21
	v_lshlrev_b32_e32 v32, 16, v22
	v_and_b32_e32 v33, 0xffff0000, v22
	v_lshlrev_b32_e32 v22, 16, v23
	v_and_b32_e32 v23, 0xffff0000, v23
	v_lshlrev_b32_e32 v34, 16, v24
	v_and_b32_e32 v35, 0xffff0000, v24
	v_lshlrev_b32_e32 v24, 16, v25
	v_and_b32_e32 v25, 0xffff0000, v25
	v_lshlrev_b32_e32 v36, 16, v26
	v_and_b32_e32 v37, 0xffff0000, v26
	v_lshlrev_b32_e32 v26, 16, v27
	v_and_b32_e32 v27, 0xffff0000, v27
	v_pk_fma_f32 v[16:17], v[16:17], v[96:97], v[20:21]
	v_pk_fma_f32 v[14:15], v[14:15], v[94:95], v[30:31]
	v_pk_fma_f32 v[12:13], v[12:13], v[92:93], v[22:23]
	v_pk_fma_f32 v[10:11], v[10:11], v[90:91], v[32:33]
	v_pk_fma_f32 v[8:9], v[8:9], v[88:89], v[24:25]
	v_pk_fma_f32 v[6:7], v[6:7], v[86:87], v[34:35]
	v_pk_fma_f32 v[20:21], v[4:5], v[84:85], v[26:27]
	v_pk_fma_f32 v[22:23], v[2:3], v[82:83], v[36:37]
	v_mul_f32_e32 v4, v15, v15
	v_mul_f32_e32 v5, v17, v17
	v_mul_f32_e32 v24, v11, v11
	v_mul_f32_e32 v25, v13, v13
	v_cvt_pk_bf16_f32 v2, v14, v15
	v_cvt_pk_bf16_f32 v3, v16, v17
	v_mul_f32_e32 v15, v7, v7
	v_mul_f32_e32 v17, v9, v9
	v_mul_f32_e32 v26, v23, v23
	v_mul_f32_e32 v27, v21, v21
	v_fmac_f32_e32 v4, v14, v14
	v_fmac_f32_e32 v5, v16, v16
	v_fmac_f32_e32 v24, v10, v10
	v_fmac_f32_e32 v25, v12, v12
	v_fmac_f32_e32 v15, v6, v6
	v_fmac_f32_e32 v17, v8, v8
	v_fmac_f32_e32 v26, v22, v22
	v_fmac_f32_e32 v27, v20, v20
	v_add_f32_e32 v4, v4, v5
	v_add_f32_e32 v5, v24, v25
	v_add_f32_e32 v14, v15, v17
	v_add_f32_e32 v15, v26, v27
	v_add_f32_e32 v4, v4, v5
	v_add_f32_e32 v5, v14, v15
	v_add_f32_e32 v14, v4, v5
	v_mov_b32_e32 v15, v14
	s_nop 1
	v_permlane16_swap_b32_e32 v14, v15
	v_cvt_pk_bf16_f32 v4, v10, v11
	v_cvt_pk_bf16_f32 v5, v12, v13
	global_store_dwordx4 v[28:29], v[2:5], off
	s_waitcnt lgkmcnt(0)
	s_nop 0
	v_add_f32_e32 v2, v14, v15
	v_mov_b32_e32 v3, v2
	s_nop 1
	v_permlane32_swap_b32_e32 v2, v3
	v_cvt_pk_bf16_f32 v4, v6, v7
	v_cvt_pk_bf16_f32 v5, v8, v9
	v_cvt_pk_bf16_f32 v6, v22, v23
	v_cvt_pk_bf16_f32 v7, v20, v21
	global_store_dwordx4 v[28:29], v[4:7], off offset:256
	s_and_saveexec_b64 s[30:31], s[0:1]
	s_cbranch_execz .LBB0_684
	v_lshlrev_b64 v[4:5], 6, v[18:19]
	v_lshl_add_u64 v[4:5], s[14:15], 0, v[4:5]
	v_lshl_add_u64 v[4:5], s[28:29], 2, v[4:5]
	s_lshl_b32 s10, s62, 2
	v_lshl_add_u64 v[4:5], v[4:5], 0, s[10:11]
	s_waitcnt lgkmcnt(0)
	v_add_f32_e32 v2, v2, v3
	global_store_dword v[4:5], v2, off

.LBB0_999:
	global_load_dwordx4 v[220:223], v[204:205], off offset:528
	s_nop 0
	global_load_dwordx4 v[206:209], v[206:207], off offset:528
	v_lshl_add_u32 v204, s44, 8, v212
	v_ashrrev_i32_e32 v205, 31, v204
	v_lshlrev_b64 v[224:225], 10, v[204:205]
	v_lshl_add_u64 v[224:225], v[224:225], 0, v[202:203]
	v_lshlrev_b64 v[232:233], 1, v[224:225]
	v_lshl_add_u64 v[234:235], s[20:21], 0, v[232:233]
	global_load_dwordx4 v[224:227], v[234:235], off
	global_load_dwordx4 v[228:231], v[234:235], off offset:256
	s_waitcnt vmcnt(0)
	v_pk_add_f32 v[180:181], v[180:181], 1.0 op_sel_hi:[1,0]
	v_pk_add_f32 v[178:179], v[178:179], 1.0 op_sel_hi:[1,0]
	v_pk_add_f32 v[172:173], v[172:173], 1.0 op_sel_hi:[1,0]
	v_pk_add_f32 v[170:171], v[170:171], 1.0 op_sel_hi:[1,0]
	v_pk_add_f32 v[182:183], v[182:183], 1.0 op_sel_hi:[1,0]
	v_pk_add_f32 v[236:237], v[160:161], v[80:81]
	v_pk_add_f32 v[238:239], v[158:159], v[78:79]
	v_pk_add_f32 v[240:241], v[156:157], v[76:77]
	v_pk_add_f32 v[242:243], v[154:155], v[74:75]
	v_pk_mul_f32 v[154:155], v[168:169], v[180:181]
	v_pk_mul_f32 v[156:157], v[166:167], v[178:179]
	v_pk_mul_f32 v[158:159], v[164:165], v[172:173]
	v_pk_mul_f32 v[160:161], v[162:163], v[170:171]
	v_pk_add_f32 v[184:185], v[184:185], 1.0 op_sel_hi:[1,0]
	v_pk_add_f32 v[246:247], v[150:151], v[94:95]
	v_pk_add_f32 v[250:251], v[146:147], v[90:91]
	v_pk_mul_f32 v[146:147], v[174:175], v[182:183]
	v_pk_add_f32 v[244:245], v[152:153], v[96:97]
	v_pk_add_f32 v[248:249], v[148:149], v[92:93]
	v_pk_mul_f32 v[152:153], v[176:177], v[184:185]
	v_lshl_add_u64 v[170:171], s[14:15], 0, v[232:233]
	s_lshl_b32 s6, s10, 2
	s_ashr_i32 s7, s6, 31
	v_pk_add_f32 v[150:151], v[206:207], 1.0 op_sel_hi:[1,0]
	v_pk_add_f32 v[148:149], v[208:209], 1.0 op_sel_hi:[1,0]
	v_pk_mul_f32 v[150:151], v[220:221], v[150:151]
	v_pk_mul_f32 v[148:149], v[222:223], v[148:149]
	v_lshlrev_b32_e32 v162, 16, v224
	v_and_b32_e32 v163, 0xffff0000, v224
	v_lshlrev_b32_e32 v164, 16, v225
	v_and_b32_e32 v165, 0xffff0000, v225
	v_lshlrev_b32_e32 v166, 16, v226
	v_and_b32_e32 v167, 0xffff0000, v226
	v_lshlrev_b32_e32 v168, 16, v227
	v_and_b32_e32 v169, 0xffff0000, v227
	v_pk_fma_f32 v[180:181], v[68:69], v[236:237], v[164:165]
	v_pk_fma_f32 v[182:183], v[66:67], v[238:239], v[162:163]
	v_pk_fma_f32 v[168:169], v[72:73], v[240:241], v[168:169]
	v_pk_fma_f32 v[166:167], v[70:71], v[242:243], v[166:167]
	v_lshlrev_b32_e32 v172, 16, v228
	v_and_b32_e32 v173, 0xffff0000, v228
	v_lshlrev_b32_e32 v174, 16, v229
	v_and_b32_e32 v175, 0xffff0000, v229
	v_lshlrev_b32_e32 v176, 16, v230
	v_and_b32_e32 v177, 0xffff0000, v230
	v_lshlrev_b32_e32 v178, 16, v231
	v_and_b32_e32 v179, 0xffff0000, v231
	v_cvt_pk_bf16_f32 v162, v182, v183
	v_cvt_pk_bf16_f32 v163, v180, v181
	v_cvt_pk_bf16_f32 v164, v166, v167
	v_cvt_pk_bf16_f32 v165, v168, v169
	v_pk_mul_f32 v[184:185], v[158:159], v[180:181]
	v_pk_mul_f32 v[206:207], v[160:161], v[182:183]
	v_pk_mul_f32 v[208:209], v[154:155], v[168:169]
	v_pk_mul_f32 v[220:221], v[156:157], v[166:167]
	v_pk_fma_f32 v[174:175], v[84:85], v[244:245], v[174:175]
	v_pk_fma_f32 v[172:173], v[82:83], v[246:247], v[172:173]
	v_pk_fma_f32 v[178:179], v[88:89], v[248:249], v[178:179]
	v_pk_fma_f32 v[176:177], v[86:87], v[250:251], v[176:177]
	global_store_dwordx4 v[234:235], v[162:165], off
	v_mul_f32_e32 v219, v183, v183
	v_mul_f32_e32 v222, v181, v181
	v_cvt_pk_bf16_f32 v162, v206, v207
	v_cvt_pk_bf16_f32 v163, v184, v185
	v_cvt_pk_bf16_f32 v164, v220, v221
	v_cvt_pk_bf16_f32 v165, v208, v209
	v_mul_f32_e32 v223, v167, v167
	v_mul_f32_e32 v224, v169, v169
	v_mul_f32_e32 v167, v173, v173
	v_mul_f32_e32 v169, v175, v175
	v_mul_f32_e32 v181, v177, v177
	global_store_dwordx4 v[170:171], v[162:165], off
	v_fmac_f32_e32 v219, v182, v182
	v_fmac_f32_e32 v222, v180, v180
	v_mul_f32_e32 v164, v179, v179
	v_fmac_f32_e32 v223, v166, v166
	v_fmac_f32_e32 v224, v168, v168
	v_fmac_f32_e32 v167, v172, v172
	v_fmac_f32_e32 v169, v174, v174
	v_fmac_f32_e32 v181, v176, v176
	v_fmac_f32_e32 v164, v178, v178
	v_add_f32_e32 v166, v219, v222
	v_add_f32_e32 v168, v223, v224
	v_add_f32_e32 v162, v167, v169
	v_add_f32_e32 v164, v181, v164
	v_add_f32_e32 v163, v166, v168
	v_add_f32_e32 v162, v162, v164
	v_add_f32_e32 v167, v163, v162
	v_cvt_pk_bf16_f32 v162, v172, v173
	v_cvt_pk_bf16_f32 v163, v174, v175
	v_cvt_pk_bf16_f32 v164, v176, v177
	v_cvt_pk_bf16_f32 v165, v178, v179
	global_store_dwordx4 v[234:235], v[162:165], off offset:256
	v_pk_mul_f32 v[168:169], v[152:153], v[174:175]
	v_pk_mul_f32 v[174:175], v[150:151], v[176:177]
	v_and_b32_e32 v163, 64, v218
	v_xor_b32_e32 v162, 16, v218
	v_add_u32_e32 v165, 64, v163
	v_cmp_lt_i32_e32 vcc, v162, v165
	s_nop 1
	v_cndmask_b32_e32 v162, v218, v162, vcc
	v_lshlrev_b32_e32 v164, 2, v162
	v_mov_b32_e32 v180, v167
	s_nop 1
	v_permlane16_swap_b32_e32 v167, v180
	v_pk_mul_f32 v[162:163], v[146:147], v[172:173]
	v_pk_mul_f32 v[172:173], v[148:149], v[178:179]
	v_cvt_pk_bf16_f32 v166, v162, v163
	v_xor_b32_e32 v163, 32, v218
	v_cmp_lt_i32_e32 vcc, v163, v165
	s_waitcnt lgkmcnt(0)
	v_add_f32_e32 v162, v167, v180
	v_cvt_pk_bf16_f32 v167, v168, v169
	v_cndmask_b32_e32 v163, v218, v163, vcc
	v_lshlrev_b32_e32 v165, 2, v163
	v_mov_b32_e32 v163, v162
	s_nop 1
	v_permlane32_swap_b32_e32 v162, v163
	v_cvt_pk_bf16_f32 v168, v174, v175
	v_cvt_pk_bf16_f32 v169, v172, v173
	global_store_dwordx4 v[170:171], v[166:169], off offset:256
	s_and_saveexec_b64 s[44:45], s[0:1]
	s_cbranch_execz .LBB0_1001
	v_lshlrev_b64 v[166:167], 6, v[204:205]
	v_lshl_add_u64 v[166:167], s[16:17], 0, v[166:167]
	v_lshl_add_u64 v[166:167], s[6:7], 2, v[166:167]
	s_lshl_b32 s10, s70, 2
	v_lshl_add_u64 v[166:167], v[166:167], 0, s[10:11]
	s_waitcnt lgkmcnt(0)
	v_add_f32_e32 v162, v162, v163
	global_store_dword v[166:167], v162, off
.LBB0_1001:
	s_or_b64 exec, exec, s[44:45]
	v_or_b32_e32 v162, 16, v204
	s_waitcnt lgkmcnt(0)
	v_ashrrev_i32_e32 v163, 31, v162
	v_lshlrev_b64 v[166:167], 10, v[162:163]
	v_lshl_add_u64 v[166:167], v[166:167], 0, v[202:203]
	v_lshlrev_b64 v[174:175], 1, v[166:167]
	v_lshl_add_u64 v[176:177], s[20:21], 0, v[174:175]
	global_load_dwordx4 v[166:169], v[176:177], off
	global_load_dwordx4 v[170:173], v[176:177], off offset:256
	v_pk_add_f32 v[144:145], v[144:145], v[80:81]
	v_pk_add_f32 v[142:143], v[142:143], v[78:79]
	v_pk_add_f32 v[140:141], v[140:141], v[76:77]
	v_pk_add_f32 v[138:139], v[138:139], v[74:75]
	v_pk_add_f32 v[136:137], v[136:137], v[96:97]
	v_pk_add_f32 v[134:135], v[134:135], v[94:95]
	v_pk_add_f32 v[132:133], v[132:133], v[92:93]
	v_pk_add_f32 v[130:131], v[130:131], v[90:91]
	v_lshl_add_u64 v[174:175], s[14:15], 0, v[174:175]
	s_waitcnt vmcnt(1)
	v_lshlrev_b32_e32 v178, 16, v166
	v_and_b32_e32 v179, 0xffff0000, v166
	v_lshlrev_b32_e32 v166, 16, v167
	v_and_b32_e32 v167, 0xffff0000, v167
	v_lshlrev_b32_e32 v180, 16, v168
	v_and_b32_e32 v181, 0xffff0000, v168
	v_lshlrev_b32_e32 v168, 16, v169
	v_and_b32_e32 v169, 0xffff0000, v169
	s_waitcnt vmcnt(0)
	v_lshlrev_b32_e32 v182, 16, v170
	v_and_b32_e32 v183, 0xffff0000, v170
	v_lshlrev_b32_e32 v170, 16, v171
	v_and_b32_e32 v171, 0xffff0000, v171
	v_lshlrev_b32_e32 v184, 16, v172
	v_and_b32_e32 v185, 0xffff0000, v172
	v_lshlrev_b32_e32 v172, 16, v173
	v_and_b32_e32 v173, 0xffff0000, v173
	v_pk_fma_f32 v[144:145], v[68:69], v[144:145], v[166:167]
	v_pk_fma_f32 v[142:143], v[66:67], v[142:143], v[178:179]
	v_pk_fma_f32 v[140:141], v[72:73], v[140:141], v[168:169]
	v_pk_fma_f32 v[138:139], v[70:71], v[138:139], v[180:181]
	v_pk_fma_f32 v[166:167], v[84:85], v[136:137], v[170:171]
	v_pk_fma_f32 v[168:169], v[82:83], v[134:135], v[182:183]
	v_pk_fma_f32 v[170:171], v[88:89], v[132:133], v[172:173]
	v_pk_fma_f32 v[172:173], v[86:87], v[130:131], v[184:185]
	v_mul_f32_e32 v205, v143, v143
	v_mul_f32_e32 v206, v145, v145
	v_mul_f32_e32 v207, v139, v139
	v_mul_f32_e32 v208, v141, v141
	v_cvt_pk_bf16_f32 v130, v142, v143
	v_cvt_pk_bf16_f32 v131, v144, v145
	v_cvt_pk_bf16_f32 v132, v138, v139
	v_cvt_pk_bf16_f32 v133, v140, v141
	v_pk_mul_f32 v[178:179], v[158:159], v[144:145]
	v_pk_mul_f32 v[180:181], v[160:161], v[142:143]
	v_pk_mul_f32 v[182:183], v[154:155], v[140:141]
	v_pk_mul_f32 v[184:185], v[156:157], v[138:139]
	v_mul_f32_e32 v139, v169, v169
	v_mul_f32_e32 v141, v167, v167
	v_mul_f32_e32 v143, v173, v173
	v_mul_f32_e32 v145, v171, v171
	v_cvt_pk_bf16_f32 v134, v168, v169
	v_cvt_pk_bf16_f32 v135, v166, v167
	v_cvt_pk_bf16_f32 v136, v172, v173
	v_cvt_pk_bf16_f32 v137, v170, v171
	v_fmac_f32_e32 v205, v142, v142
	v_fmac_f32_e32 v206, v144, v144
	v_fmac_f32_e32 v207, v138, v138
	v_fmac_f32_e32 v208, v140, v140
	global_store_dwordx4 v[176:177], v[130:133], off
	v_fmac_f32_e32 v139, v168, v168
	v_fmac_f32_e32 v141, v166, v166
	v_cvt_pk_bf16_f32 v130, v180, v181
	v_cvt_pk_bf16_f32 v131, v178, v179
	v_cvt_pk_bf16_f32 v132, v184, v185
	v_cvt_pk_bf16_f32 v133, v182, v183
	v_fmac_f32_e32 v143, v172, v172
	v_fmac_f32_e32 v145, v170, v170
	global_store_dwordx4 v[176:177], v[134:137], off offset:256
	global_store_dwordx4 v[174:175], v[130:133], off
	s_nop 0
	v_add_f32_e32 v134, v205, v206
	v_add_f32_e32 v135, v207, v208
	v_add_f32_e32 v130, v139, v141
	v_add_f32_e32 v131, v143, v145
	v_add_f32_e32 v132, v134, v135
	v_add_f32_e32 v130, v130, v131
	v_add_f32_e32 v133, v132, v130
	v_mov_b32_e32 v140, v133
	s_nop 1
	v_permlane16_swap_b32_e32 v133, v140
	v_pk_mul_f32 v[130:131], v[146:147], v[168:169]
	v_pk_mul_f32 v[134:135], v[152:153], v[166:167]
	v_cvt_pk_bf16_f32 v132, v130, v131
	v_pk_mul_f32 v[136:137], v[148:149], v[170:171]
	s_waitcnt lgkmcnt(0)
	v_add_f32_e32 v130, v133, v140
	v_mov_b32_e32 v131, v130
	s_nop 1
	v_permlane32_swap_b32_e32 v130, v131
	v_pk_mul_f32 v[138:139], v[150:151], v[172:173]
	v_cvt_pk_bf16_f32 v133, v134, v135
	v_cvt_pk_bf16_f32 v134, v138, v139
	v_cvt_pk_bf16_f32 v135, v136, v137
	global_store_dwordx4 v[174:175], v[132:135], off offset:256
	s_and_saveexec_b64 s[44:45], s[0:1]
	s_cbranch_execz .LBB0_1003
	v_lshlrev_b64 v[132:133], 6, v[162:163]
	v_lshl_add_u64 v[132:133], s[16:17], 0, v[132:133]
	v_lshl_add_u64 v[132:133], s[6:7], 2, v[132:133]
	s_lshl_b32 s10, s70, 2
	v_lshl_add_u64 v[132:133], v[132:133], 0, s[10:11]
	s_waitcnt lgkmcnt(0)
	v_add_f32_e32 v130, v130, v131
	global_store_dword v[132:133], v130, off
.LBB0_1003:
	s_or_b64 exec, exec, s[44:45]
	v_or_b32_e32 v130, 32, v204
	s_waitcnt lgkmcnt(0)
	v_ashrrev_i32_e32 v131, 31, v130
	v_lshlrev_b64 v[132:133], 10, v[130:131]
	v_lshl_add_u64 v[132:133], v[132:133], 0, v[202:203]
	v_lshlrev_b64 v[140:141], 1, v[132:133]
	v_lshl_add_u64 v[142:143], s[20:21], 0, v[140:141]
	global_load_dwordx4 v[132:135], v[142:143], off
	global_load_dwordx4 v[136:139], v[142:143], off offset:256
	v_pk_add_f32 v[128:129], v[128:129], v[80:81]
	v_pk_add_f32 v[126:127], v[126:127], v[78:79]
	v_pk_add_f32 v[124:125], v[124:125], v[76:77]
	v_pk_add_f32 v[122:123], v[122:123], v[74:75]
	v_pk_add_f32 v[120:121], v[120:121], v[96:97]
	v_pk_add_f32 v[118:119], v[118:119], v[94:95]
	v_pk_add_f32 v[116:117], v[116:117], v[92:93]
	v_pk_add_f32 v[114:115], v[114:115], v[90:91]
	v_lshl_add_u64 v[140:141], s[14:15], 0, v[140:141]
	s_waitcnt vmcnt(1)
	v_lshlrev_b32_e32 v144, 16, v132
	v_and_b32_e32 v145, 0xffff0000, v132
	v_lshlrev_b32_e32 v132, 16, v133
	v_and_b32_e32 v133, 0xffff0000, v133
	v_lshlrev_b32_e32 v162, 16, v134
	v_and_b32_e32 v163, 0xffff0000, v134
	v_lshlrev_b32_e32 v134, 16, v135
	v_and_b32_e32 v135, 0xffff0000, v135
	s_waitcnt vmcnt(0)
	v_lshlrev_b32_e32 v166, 16, v136
	v_and_b32_e32 v167, 0xffff0000, v136
	v_lshlrev_b32_e32 v136, 16, v137
	v_and_b32_e32 v137, 0xffff0000, v137
	v_lshlrev_b32_e32 v168, 16, v138
	v_and_b32_e32 v169, 0xffff0000, v138
	v_lshlrev_b32_e32 v138, 16, v139
	v_and_b32_e32 v139, 0xffff0000, v139
	v_pk_fma_f32 v[128:129], v[68:69], v[128:129], v[132:133]
	v_pk_fma_f32 v[126:127], v[66:67], v[126:127], v[144:145]
	v_pk_fma_f32 v[124:125], v[72:73], v[124:125], v[134:135]
	v_pk_fma_f32 v[122:123], v[70:71], v[122:123], v[162:163]
	v_pk_fma_f32 v[132:133], v[84:85], v[120:121], v[136:137]
	v_pk_fma_f32 v[134:135], v[82:83], v[118:119], v[166:167]
	v_pk_fma_f32 v[136:137], v[88:89], v[116:117], v[138:139]
	v_pk_fma_f32 v[138:139], v[86:87], v[114:115], v[168:169]
	v_mul_f32_e32 v170, v127, v127
	v_mul_f32_e32 v171, v129, v129
	v_mul_f32_e32 v172, v123, v123
	v_mul_f32_e32 v173, v125, v125
	v_cvt_pk_bf16_f32 v114, v126, v127
	v_cvt_pk_bf16_f32 v115, v128, v129
	v_cvt_pk_bf16_f32 v116, v122, v123
	v_cvt_pk_bf16_f32 v117, v124, v125
	v_pk_mul_f32 v[144:145], v[158:159], v[128:129]
	v_pk_mul_f32 v[162:163], v[160:161], v[126:127]
	v_pk_mul_f32 v[166:167], v[154:155], v[124:125]
	v_pk_mul_f32 v[168:169], v[156:157], v[122:123]
	v_mul_f32_e32 v123, v135, v135
	v_mul_f32_e32 v125, v133, v133
	v_mul_f32_e32 v127, v139, v139
	v_mul_f32_e32 v129, v137, v137
	v_cvt_pk_bf16_f32 v118, v134, v135
	v_cvt_pk_bf16_f32 v119, v132, v133
	v_cvt_pk_bf16_f32 v120, v138, v139
	v_cvt_pk_bf16_f32 v121, v136, v137
	v_fmac_f32_e32 v170, v126, v126
	v_fmac_f32_e32 v171, v128, v128
	v_fmac_f32_e32 v172, v122, v122
	v_fmac_f32_e32 v173, v124, v124
	global_store_dwordx4 v[142:143], v[114:117], off
	v_fmac_f32_e32 v123, v134, v134
	v_fmac_f32_e32 v125, v132, v132
	v_cvt_pk_bf16_f32 v114, v162, v163
	v_cvt_pk_bf16_f32 v115, v144, v145
	v_cvt_pk_bf16_f32 v116, v168, v169
	v_cvt_pk_bf16_f32 v117, v166, v167
	v_fmac_f32_e32 v127, v138, v138
	v_fmac_f32_e32 v129, v136, v136
	global_store_dwordx4 v[142:143], v[118:121], off offset:256
	global_store_dwordx4 v[140:141], v[114:117], off
	s_nop 0
	v_add_f32_e32 v118, v170, v171
	v_add_f32_e32 v119, v172, v173
	v_add_f32_e32 v114, v123, v125
	v_add_f32_e32 v115, v127, v129
	v_add_f32_e32 v116, v118, v119
	v_add_f32_e32 v114, v114, v115
	v_add_f32_e32 v117, v116, v114
	v_mov_b32_e32 v124, v117
	s_nop 1
	v_permlane16_swap_b32_e32 v117, v124
	v_pk_mul_f32 v[114:115], v[146:147], v[134:135]
	v_pk_mul_f32 v[118:119], v[152:153], v[132:133]
	v_cvt_pk_bf16_f32 v116, v114, v115
	v_pk_mul_f32 v[120:121], v[148:149], v[136:137]
	s_waitcnt lgkmcnt(0)
	v_add_f32_e32 v114, v117, v124
	v_mov_b32_e32 v115, v114
	s_nop 1
	v_permlane32_swap_b32_e32 v114, v115
	v_pk_mul_f32 v[122:123], v[150:151], v[138:139]
	v_cvt_pk_bf16_f32 v117, v118, v119
	v_cvt_pk_bf16_f32 v118, v122, v123
	v_cvt_pk_bf16_f32 v119, v120, v121
	global_store_dwordx4 v[140:141], v[116:119], off offset:256
	s_and_saveexec_b64 s[44:45], s[0:1]
	s_cbranch_execz .LBB0_1005
	v_lshlrev_b64 v[116:117], 6, v[130:131]
	v_lshl_add_u64 v[116:117], s[16:17], 0, v[116:117]
	v_lshl_add_u64 v[116:117], s[6:7], 2, v[116:117]
	s_lshl_b32 s10, s70, 2
	v_lshl_add_u64 v[116:117], v[116:117], 0, s[10:11]
	s_waitcnt lgkmcnt(0)
	v_add_f32_e32 v114, v114, v115
	global_store_dword v[116:117], v114, off
.LBB0_1005:
	s_or_b64 exec, exec, s[44:45]
	v_or_b32_e32 v114, 48, v204
	s_waitcnt lgkmcnt(0)
	v_ashrrev_i32_e32 v115, 31, v114
	v_lshlrev_b64 v[116:117], 10, v[114:115]
	v_lshl_add_u64 v[116:117], v[116:117], 0, v[202:203]
	v_lshlrev_b64 v[124:125], 1, v[116:117]
	v_lshl_add_u64 v[126:127], s[20:21], 0, v[124:125]
	global_load_dwordx4 v[116:119], v[126:127], off
	global_load_dwordx4 v[120:123], v[126:127], off offset:256
	v_pk_add_f32 v[112:113], v[112:113], v[80:81]
	v_pk_add_f32 v[110:111], v[110:111], v[78:79]
	v_pk_add_f32 v[108:109], v[108:109], v[76:77]
	v_pk_add_f32 v[106:107], v[106:107], v[74:75]
	v_pk_add_f32 v[104:105], v[104:105], v[96:97]
	v_pk_add_f32 v[102:103], v[102:103], v[94:95]
	v_pk_add_f32 v[100:101], v[100:101], v[92:93]
	v_pk_add_f32 v[98:99], v[98:99], v[90:91]
	v_lshl_add_u64 v[124:125], s[14:15], 0, v[124:125]
	s_waitcnt vmcnt(1)
	v_lshlrev_b32_e32 v128, 16, v116
	v_and_b32_e32 v129, 0xffff0000, v116
	v_lshlrev_b32_e32 v116, 16, v117
	v_and_b32_e32 v117, 0xffff0000, v117
	v_lshlrev_b32_e32 v130, 16, v118
	v_and_b32_e32 v131, 0xffff0000, v118
	v_lshlrev_b32_e32 v118, 16, v119
	v_and_b32_e32 v119, 0xffff0000, v119
	s_waitcnt vmcnt(0)
	v_lshlrev_b32_e32 v132, 16, v120
	v_and_b32_e32 v133, 0xffff0000, v120
	v_lshlrev_b32_e32 v120, 16, v121
	v_and_b32_e32 v121, 0xffff0000, v121
	v_lshlrev_b32_e32 v134, 16, v122
	v_and_b32_e32 v135, 0xffff0000, v122
	v_lshlrev_b32_e32 v122, 16, v123
	v_and_b32_e32 v123, 0xffff0000, v123
	v_pk_fma_f32 v[112:113], v[68:69], v[112:113], v[116:117]
	v_pk_fma_f32 v[110:111], v[66:67], v[110:111], v[128:129]
	v_pk_fma_f32 v[108:109], v[72:73], v[108:109], v[118:119]
	v_pk_fma_f32 v[106:107], v[70:71], v[106:107], v[130:131]
	v_pk_fma_f32 v[116:117], v[84:85], v[104:105], v[120:121]
	v_pk_fma_f32 v[118:119], v[82:83], v[102:103], v[132:133]
	v_pk_fma_f32 v[120:121], v[88:89], v[100:101], v[122:123]
	v_pk_fma_f32 v[122:123], v[86:87], v[98:99], v[134:135]
	v_mul_f32_e32 v136, v111, v111
	v_mul_f32_e32 v137, v113, v113
	v_mul_f32_e32 v138, v107, v107
	v_mul_f32_e32 v139, v109, v109
	v_cvt_pk_bf16_f32 v98, v110, v111
	v_cvt_pk_bf16_f32 v99, v112, v113
	v_cvt_pk_bf16_f32 v100, v106, v107
	v_cvt_pk_bf16_f32 v101, v108, v109
	v_pk_mul_f32 v[128:129], v[158:159], v[112:113]
	v_pk_mul_f32 v[130:131], v[160:161], v[110:111]
	v_pk_mul_f32 v[132:133], v[154:155], v[108:109]
	v_pk_mul_f32 v[134:135], v[156:157], v[106:107]
	v_mul_f32_e32 v107, v119, v119
	v_mul_f32_e32 v109, v117, v117
	v_mul_f32_e32 v111, v123, v123
	v_mul_f32_e32 v113, v121, v121
	v_cvt_pk_bf16_f32 v102, v118, v119
	v_cvt_pk_bf16_f32 v103, v116, v117
	v_cvt_pk_bf16_f32 v104, v122, v123
	v_cvt_pk_bf16_f32 v105, v120, v121
	v_fmac_f32_e32 v136, v110, v110
	v_fmac_f32_e32 v137, v112, v112
	v_fmac_f32_e32 v138, v106, v106
	v_fmac_f32_e32 v139, v108, v108
	global_store_dwordx4 v[126:127], v[98:101], off
	v_fmac_f32_e32 v107, v118, v118
	v_fmac_f32_e32 v109, v116, v116
	v_cvt_pk_bf16_f32 v98, v130, v131
	v_cvt_pk_bf16_f32 v99, v128, v129
	v_cvt_pk_bf16_f32 v100, v134, v135
	v_cvt_pk_bf16_f32 v101, v132, v133
	v_fmac_f32_e32 v111, v122, v122
	v_fmac_f32_e32 v113, v120, v120
	global_store_dwordx4 v[126:127], v[102:105], off offset:256
	global_store_dwordx4 v[124:125], v[98:101], off
	s_nop 0
	v_add_f32_e32 v102, v136, v137
	v_add_f32_e32 v103, v138, v139
	v_add_f32_e32 v98, v107, v109
	v_add_f32_e32 v99, v111, v113
	v_add_f32_e32 v100, v102, v103
	v_add_f32_e32 v98, v98, v99
	v_add_f32_e32 v101, v100, v98
	v_mov_b32_e32 v108, v101
	s_nop 1
	v_permlane16_swap_b32_e32 v101, v108
	v_pk_mul_f32 v[98:99], v[146:147], v[118:119]
	v_pk_mul_f32 v[102:103], v[152:153], v[116:117]
	v_cvt_pk_bf16_f32 v100, v98, v99
	v_pk_mul_f32 v[104:105], v[148:149], v[120:121]
	s_waitcnt lgkmcnt(0)
	v_add_f32_e32 v98, v101, v108
	v_mov_b32_e32 v99, v98
	s_nop 1
	v_permlane32_swap_b32_e32 v98, v99
	v_pk_mul_f32 v[106:107], v[150:151], v[122:123]
	v_cvt_pk_bf16_f32 v101, v102, v103
	v_cvt_pk_bf16_f32 v102, v106, v107
	v_cvt_pk_bf16_f32 v103, v104, v105
	global_store_dwordx4 v[124:125], v[100:103], off offset:256
	s_and_saveexec_b64 s[44:45], s[0:1]
	s_cbranch_execz .LBB0_1007
	v_lshlrev_b64 v[100:101], 6, v[114:115]
	v_lshl_add_u64 v[100:101], s[16:17], 0, v[100:101]
	v_lshl_add_u64 v[100:101], s[6:7], 2, v[100:101]
	s_lshl_b32 s10, s70, 2
	v_lshl_add_u64 v[100:101], v[100:101], 0, s[10:11]
	s_waitcnt lgkmcnt(0)
	v_add_f32_e32 v98, v98, v99
	global_store_dword v[100:101], v98, off
.LBB0_1007:
	s_or_b64 exec, exec, s[44:45]
	v_add_u32_e32 v98, 0x80, v204
	s_waitcnt lgkmcnt(0)
	v_ashrrev_i32_e32 v99, 31, v98
	v_lshlrev_b64 v[100:101], 10, v[98:99]
	v_lshl_add_u64 v[100:101], v[100:101], 0, v[202:203]
	v_lshlrev_b64 v[108:109], 1, v[100:101]
	v_lshl_add_u64 v[110:111], s[20:21], 0, v[108:109]
	global_load_dwordx4 v[100:103], v[110:111], off
	global_load_dwordx4 v[104:107], v[110:111], off offset:256
	v_pk_add_f32 v[64:65], v[64:65], v[80:81]
	v_pk_add_f32 v[62:63], v[62:63], v[78:79]
	v_pk_add_f32 v[60:61], v[60:61], v[76:77]
	v_pk_add_f32 v[58:59], v[58:59], v[74:75]
	v_pk_add_f32 v[56:57], v[56:57], v[96:97]
	v_pk_add_f32 v[54:55], v[54:55], v[94:95]
	v_pk_add_f32 v[52:53], v[52:53], v[92:93]
	v_pk_add_f32 v[50:51], v[50:51], v[90:91]
	v_lshl_add_u64 v[108:109], s[14:15], 0, v[108:109]
	s_waitcnt vmcnt(1)
	v_lshlrev_b32_e32 v112, 16, v100
	v_and_b32_e32 v113, 0xffff0000, v100
	v_lshlrev_b32_e32 v100, 16, v101
	v_and_b32_e32 v101, 0xffff0000, v101
	v_lshlrev_b32_e32 v114, 16, v102
	v_and_b32_e32 v115, 0xffff0000, v102
	v_lshlrev_b32_e32 v102, 16, v103
	v_and_b32_e32 v103, 0xffff0000, v103
	s_waitcnt vmcnt(0)
	v_lshlrev_b32_e32 v116, 16, v104
	v_and_b32_e32 v117, 0xffff0000, v104
	v_lshlrev_b32_e32 v104, 16, v105
	v_and_b32_e32 v105, 0xffff0000, v105
	v_lshlrev_b32_e32 v118, 16, v106
	v_and_b32_e32 v119, 0xffff0000, v106
	v_lshlrev_b32_e32 v106, 16, v107
	v_and_b32_e32 v107, 0xffff0000, v107
	v_pk_fma_f32 v[64:65], v[68:69], v[64:65], v[100:101]
	v_pk_fma_f32 v[62:63], v[66:67], v[62:63], v[112:113]
	v_pk_fma_f32 v[60:61], v[72:73], v[60:61], v[102:103]
	v_pk_fma_f32 v[58:59], v[70:71], v[58:59], v[114:115]
	v_pk_fma_f32 v[100:101], v[84:85], v[56:57], v[104:105]
	v_pk_fma_f32 v[102:103], v[82:83], v[54:55], v[116:117]
	v_pk_fma_f32 v[104:105], v[88:89], v[52:53], v[106:107]
	v_pk_fma_f32 v[106:107], v[86:87], v[50:51], v[118:119]
	v_mul_f32_e32 v120, v63, v63
	v_mul_f32_e32 v121, v65, v65
	v_mul_f32_e32 v122, v59, v59
	v_mul_f32_e32 v123, v61, v61
	v_cvt_pk_bf16_f32 v50, v62, v63
	v_cvt_pk_bf16_f32 v51, v64, v65
	v_cvt_pk_bf16_f32 v52, v58, v59
	v_cvt_pk_bf16_f32 v53, v60, v61
	v_pk_mul_f32 v[112:113], v[158:159], v[64:65]
	v_pk_mul_f32 v[114:115], v[160:161], v[62:63]
	v_pk_mul_f32 v[116:117], v[154:155], v[60:61]
	v_pk_mul_f32 v[118:119], v[156:157], v[58:59]
	v_mul_f32_e32 v59, v103, v103
	v_mul_f32_e32 v61, v101, v101
	v_mul_f32_e32 v63, v107, v107
	v_mul_f32_e32 v65, v105, v105
	v_cvt_pk_bf16_f32 v54, v102, v103
	v_cvt_pk_bf16_f32 v55, v100, v101
	v_cvt_pk_bf16_f32 v56, v106, v107
	v_cvt_pk_bf16_f32 v57, v104, v105
	v_fmac_f32_e32 v120, v62, v62
	v_fmac_f32_e32 v121, v64, v64
	v_fmac_f32_e32 v122, v58, v58
	v_fmac_f32_e32 v123, v60, v60
	global_store_dwordx4 v[110:111], v[50:53], off
	v_fmac_f32_e32 v59, v102, v102
	v_fmac_f32_e32 v61, v100, v100
	v_cvt_pk_bf16_f32 v50, v114, v115
	v_cvt_pk_bf16_f32 v51, v112, v113
	v_cvt_pk_bf16_f32 v52, v118, v119
	v_cvt_pk_bf16_f32 v53, v116, v117
	v_fmac_f32_e32 v63, v106, v106
	v_fmac_f32_e32 v65, v104, v104
	global_store_dwordx4 v[110:111], v[54:57], off offset:256
	global_store_dwordx4 v[108:109], v[50:53], off
	s_nop 0
	v_add_f32_e32 v54, v120, v121
	v_add_f32_e32 v55, v122, v123
	v_add_f32_e32 v50, v59, v61
	v_add_f32_e32 v51, v63, v65
	v_add_f32_e32 v52, v54, v55
	v_add_f32_e32 v50, v50, v51
	v_add_f32_e32 v53, v52, v50
	v_mov_b32_e32 v60, v53
	s_nop 1
	v_permlane16_swap_b32_e32 v53, v60
	v_pk_mul_f32 v[50:51], v[146:147], v[102:103]
	v_pk_mul_f32 v[54:55], v[152:153], v[100:101]
	v_cvt_pk_bf16_f32 v52, v50, v51
	v_pk_mul_f32 v[56:57], v[148:149], v[104:105]
	s_waitcnt lgkmcnt(0)
	v_add_f32_e32 v50, v53, v60
	v_mov_b32_e32 v51, v50
	s_nop 1
	v_permlane32_swap_b32_e32 v50, v51
	v_pk_mul_f32 v[58:59], v[150:151], v[106:107]
	v_cvt_pk_bf16_f32 v53, v54, v55
	v_cvt_pk_bf16_f32 v54, v58, v59
	v_cvt_pk_bf16_f32 v55, v56, v57
	global_store_dwordx4 v[108:109], v[52:55], off offset:256
	s_and_saveexec_b64 s[44:45], s[0:1]
	s_cbranch_execz .LBB0_1009
	v_lshlrev_b64 v[52:53], 6, v[98:99]
	v_lshl_add_u64 v[52:53], s[16:17], 0, v[52:53]
	v_lshl_add_u64 v[52:53], s[6:7], 2, v[52:53]
	s_lshl_b32 s10, s70, 2
	v_lshl_add_u64 v[52:53], v[52:53], 0, s[10:11]
	s_waitcnt lgkmcnt(0)
	v_add_f32_e32 v50, v50, v51
	global_store_dword v[52:53], v50, off
.LBB0_1009:
	s_or_b64 exec, exec, s[44:45]
	v_add_u32_e32 v50, 0x90, v204
	s_waitcnt lgkmcnt(0)
	v_ashrrev_i32_e32 v51, 31, v50
	v_lshlrev_b64 v[52:53], 10, v[50:51]
	v_lshl_add_u64 v[52:53], v[52:53], 0, v[202:203]
	v_lshlrev_b64 v[60:61], 1, v[52:53]
	v_lshl_add_u64 v[62:63], s[20:21], 0, v[60:61]
	global_load_dwordx4 v[52:55], v[62:63], off
	global_load_dwordx4 v[56:59], v[62:63], off offset:256
	v_pk_add_f32 v[48:49], v[48:49], v[80:81]
	v_pk_add_f32 v[46:47], v[46:47], v[78:79]
	v_pk_add_f32 v[44:45], v[44:45], v[76:77]
	v_pk_add_f32 v[42:43], v[42:43], v[74:75]
	v_pk_add_f32 v[40:41], v[40:41], v[96:97]
	v_pk_add_f32 v[38:39], v[38:39], v[94:95]
	v_pk_add_f32 v[36:37], v[36:37], v[92:93]
	v_pk_add_f32 v[34:35], v[34:35], v[90:91]
	v_lshl_add_u64 v[60:61], s[14:15], 0, v[60:61]
	s_waitcnt vmcnt(1)
	v_lshlrev_b32_e32 v64, 16, v52
	v_and_b32_e32 v65, 0xffff0000, v52
	v_lshlrev_b32_e32 v52, 16, v53
	v_and_b32_e32 v53, 0xffff0000, v53
	v_lshlrev_b32_e32 v98, 16, v54
	v_and_b32_e32 v99, 0xffff0000, v54
	v_lshlrev_b32_e32 v54, 16, v55
	v_and_b32_e32 v55, 0xffff0000, v55
	s_waitcnt vmcnt(0)
	v_lshlrev_b32_e32 v100, 16, v56
	v_and_b32_e32 v101, 0xffff0000, v56
	v_lshlrev_b32_e32 v56, 16, v57
	v_and_b32_e32 v57, 0xffff0000, v57
	v_lshlrev_b32_e32 v102, 16, v58
	v_and_b32_e32 v103, 0xffff0000, v58
	v_lshlrev_b32_e32 v58, 16, v59
	v_and_b32_e32 v59, 0xffff0000, v59
	v_pk_fma_f32 v[48:49], v[68:69], v[48:49], v[52:53]
	v_pk_fma_f32 v[46:47], v[66:67], v[46:47], v[64:65]
	v_pk_fma_f32 v[44:45], v[72:73], v[44:45], v[54:55]
	v_pk_fma_f32 v[42:43], v[70:71], v[42:43], v[98:99]
	v_pk_fma_f32 v[52:53], v[84:85], v[40:41], v[56:57]
	v_pk_fma_f32 v[54:55], v[82:83], v[38:39], v[100:101]
	v_pk_fma_f32 v[56:57], v[88:89], v[36:37], v[58:59]
	v_pk_fma_f32 v[58:59], v[86:87], v[34:35], v[102:103]
	v_mul_f32_e32 v104, v47, v47
	v_mul_f32_e32 v105, v49, v49
	v_mul_f32_e32 v106, v43, v43
	v_mul_f32_e32 v107, v45, v45
	v_cvt_pk_bf16_f32 v34, v46, v47
	v_cvt_pk_bf16_f32 v35, v48, v49
	v_cvt_pk_bf16_f32 v36, v42, v43
	v_cvt_pk_bf16_f32 v37, v44, v45
	v_pk_mul_f32 v[64:65], v[158:159], v[48:49]
	v_pk_mul_f32 v[98:99], v[160:161], v[46:47]
	v_pk_mul_f32 v[100:101], v[154:155], v[44:45]
	v_pk_mul_f32 v[102:103], v[156:157], v[42:43]
	v_mul_f32_e32 v43, v55, v55
	v_mul_f32_e32 v45, v53, v53
	v_mul_f32_e32 v47, v59, v59
	v_mul_f32_e32 v49, v57, v57
	v_cvt_pk_bf16_f32 v38, v54, v55
	v_cvt_pk_bf16_f32 v39, v52, v53
	v_cvt_pk_bf16_f32 v40, v58, v59
	v_cvt_pk_bf16_f32 v41, v56, v57
	v_fmac_f32_e32 v104, v46, v46
	v_fmac_f32_e32 v105, v48, v48
	v_fmac_f32_e32 v106, v42, v42
	v_fmac_f32_e32 v107, v44, v44
	global_store_dwordx4 v[62:63], v[34:37], off
	v_fmac_f32_e32 v43, v54, v54
	v_fmac_f32_e32 v45, v52, v52
	v_cvt_pk_bf16_f32 v34, v98, v99
	v_cvt_pk_bf16_f32 v35, v64, v65
	v_cvt_pk_bf16_f32 v36, v102, v103
	v_cvt_pk_bf16_f32 v37, v100, v101
	v_fmac_f32_e32 v47, v58, v58
	v_fmac_f32_e32 v49, v56, v56
	global_store_dwordx4 v[62:63], v[38:41], off offset:256
	global_store_dwordx4 v[60:61], v[34:37], off
	s_nop 0
	v_add_f32_e32 v38, v104, v105
	v_add_f32_e32 v39, v106, v107
	v_add_f32_e32 v34, v43, v45
	v_add_f32_e32 v35, v47, v49
	v_add_f32_e32 v36, v38, v39
	v_add_f32_e32 v34, v34, v35
	v_add_f32_e32 v37, v36, v34
	v_mov_b32_e32 v44, v37
	s_nop 1
	v_permlane16_swap_b32_e32 v37, v44
	v_pk_mul_f32 v[34:35], v[146:147], v[54:55]
	v_pk_mul_f32 v[38:39], v[152:153], v[52:53]
	v_cvt_pk_bf16_f32 v36, v34, v35
	v_pk_mul_f32 v[40:41], v[148:149], v[56:57]
	s_waitcnt lgkmcnt(0)
	v_add_f32_e32 v34, v37, v44
	v_mov_b32_e32 v35, v34
	s_nop 1
	v_permlane32_swap_b32_e32 v34, v35
	v_pk_mul_f32 v[42:43], v[150:151], v[58:59]
	v_cvt_pk_bf16_f32 v37, v38, v39
	v_cvt_pk_bf16_f32 v38, v42, v43
	v_cvt_pk_bf16_f32 v39, v40, v41
	global_store_dwordx4 v[60:61], v[36:39], off offset:256
	s_and_saveexec_b64 s[44:45], s[0:1]
	s_cbranch_execz .LBB0_1011
	v_lshlrev_b64 v[36:37], 6, v[50:51]
	v_lshl_add_u64 v[36:37], s[16:17], 0, v[36:37]
	v_lshl_add_u64 v[36:37], s[6:7], 2, v[36:37]
	s_lshl_b32 s10, s70, 2
	v_lshl_add_u64 v[36:37], v[36:37], 0, s[10:11]
	s_waitcnt lgkmcnt(0)
	v_add_f32_e32 v34, v34, v35
	global_store_dword v[36:37], v34, off
.LBB0_1011:
	s_or_b64 exec, exec, s[44:45]
	v_add_u32_e32 v34, 0xa0, v204
	s_waitcnt lgkmcnt(0)
	v_ashrrev_i32_e32 v35, 31, v34
	v_lshlrev_b64 v[36:37], 10, v[34:35]
	v_lshl_add_u64 v[36:37], v[36:37], 0, v[202:203]
	v_lshlrev_b64 v[44:45], 1, v[36:37]
	v_lshl_add_u64 v[46:47], s[20:21], 0, v[44:45]
	global_load_dwordx4 v[36:39], v[46:47], off
	global_load_dwordx4 v[40:43], v[46:47], off offset:256
	v_pk_add_f32 v[32:33], v[32:33], v[80:81]
	v_pk_add_f32 v[30:31], v[30:31], v[78:79]
	v_pk_add_f32 v[28:29], v[28:29], v[76:77]
	v_pk_add_f32 v[26:27], v[26:27], v[74:75]
	v_pk_add_f32 v[24:25], v[24:25], v[96:97]
	v_pk_add_f32 v[22:23], v[22:23], v[94:95]
	v_pk_add_f32 v[20:21], v[20:21], v[92:93]
	v_pk_add_f32 v[18:19], v[18:19], v[90:91]
	v_lshl_add_u64 v[44:45], s[14:15], 0, v[44:45]
	s_waitcnt vmcnt(1)
	v_lshlrev_b32_e32 v48, 16, v36
	v_and_b32_e32 v49, 0xffff0000, v36
	v_lshlrev_b32_e32 v36, 16, v37
	v_and_b32_e32 v37, 0xffff0000, v37
	v_lshlrev_b32_e32 v50, 16, v38
	v_and_b32_e32 v51, 0xffff0000, v38
	v_lshlrev_b32_e32 v38, 16, v39
	v_and_b32_e32 v39, 0xffff0000, v39
	s_waitcnt vmcnt(0)
	v_lshlrev_b32_e32 v52, 16, v40
	v_and_b32_e32 v53, 0xffff0000, v40
	v_lshlrev_b32_e32 v40, 16, v41
	v_and_b32_e32 v41, 0xffff0000, v41
	v_lshlrev_b32_e32 v54, 16, v42
	v_and_b32_e32 v55, 0xffff0000, v42
	v_lshlrev_b32_e32 v42, 16, v43
	v_and_b32_e32 v43, 0xffff0000, v43
	v_pk_fma_f32 v[32:33], v[68:69], v[32:33], v[36:37]
	v_pk_fma_f32 v[30:31], v[66:67], v[30:31], v[48:49]
	v_pk_fma_f32 v[28:29], v[72:73], v[28:29], v[38:39]
	v_pk_fma_f32 v[26:27], v[70:71], v[26:27], v[50:51]
	v_pk_fma_f32 v[36:37], v[84:85], v[24:25], v[40:41]
	v_pk_fma_f32 v[38:39], v[82:83], v[22:23], v[52:53]
	v_pk_fma_f32 v[40:41], v[88:89], v[20:21], v[42:43]
	v_pk_fma_f32 v[42:43], v[86:87], v[18:19], v[54:55]
	v_mul_f32_e32 v56, v31, v31
	v_mul_f32_e32 v57, v33, v33
	v_mul_f32_e32 v58, v27, v27
	v_mul_f32_e32 v59, v29, v29
	v_cvt_pk_bf16_f32 v18, v30, v31
	v_cvt_pk_bf16_f32 v19, v32, v33
	v_cvt_pk_bf16_f32 v20, v26, v27
	v_cvt_pk_bf16_f32 v21, v28, v29
	v_pk_mul_f32 v[48:49], v[158:159], v[32:33]
	v_pk_mul_f32 v[50:51], v[160:161], v[30:31]
	v_pk_mul_f32 v[52:53], v[154:155], v[28:29]
	v_pk_mul_f32 v[54:55], v[156:157], v[26:27]
	v_mul_f32_e32 v27, v39, v39
	v_mul_f32_e32 v29, v37, v37
	v_mul_f32_e32 v31, v43, v43
	v_mul_f32_e32 v33, v41, v41
	v_cvt_pk_bf16_f32 v22, v38, v39
	v_cvt_pk_bf16_f32 v23, v36, v37
	v_cvt_pk_bf16_f32 v24, v42, v43
	v_cvt_pk_bf16_f32 v25, v40, v41
	v_fmac_f32_e32 v56, v30, v30
	v_fmac_f32_e32 v57, v32, v32
	v_fmac_f32_e32 v58, v26, v26
	v_fmac_f32_e32 v59, v28, v28
	global_store_dwordx4 v[46:47], v[18:21], off
	v_fmac_f32_e32 v27, v38, v38
	v_fmac_f32_e32 v29, v36, v36
	v_cvt_pk_bf16_f32 v18, v50, v51
	v_cvt_pk_bf16_f32 v19, v48, v49
	v_cvt_pk_bf16_f32 v20, v54, v55
	v_cvt_pk_bf16_f32 v21, v52, v53
	v_fmac_f32_e32 v31, v42, v42
	v_fmac_f32_e32 v33, v40, v40
	global_store_dwordx4 v[46:47], v[22:25], off offset:256
	global_store_dwordx4 v[44:45], v[18:21], off
	s_nop 0
	v_add_f32_e32 v22, v56, v57
	v_add_f32_e32 v23, v58, v59
	v_add_f32_e32 v18, v27, v29
	v_add_f32_e32 v19, v31, v33
	v_add_f32_e32 v20, v22, v23
	v_add_f32_e32 v18, v18, v19
	v_add_f32_e32 v21, v20, v18
	v_mov_b32_e32 v28, v21
	s_nop 1
	v_permlane16_swap_b32_e32 v21, v28
	v_pk_mul_f32 v[18:19], v[146:147], v[38:39]
	v_pk_mul_f32 v[22:23], v[152:153], v[36:37]
	v_cvt_pk_bf16_f32 v20, v18, v19
	v_pk_mul_f32 v[24:25], v[148:149], v[40:41]
	s_waitcnt lgkmcnt(0)
	v_add_f32_e32 v18, v21, v28
	v_mov_b32_e32 v19, v18
	s_nop 1
	v_permlane32_swap_b32_e32 v18, v19
	v_pk_mul_f32 v[26:27], v[150:151], v[42:43]
	v_cvt_pk_bf16_f32 v21, v22, v23
	v_cvt_pk_bf16_f32 v22, v26, v27
	v_cvt_pk_bf16_f32 v23, v24, v25
	global_store_dwordx4 v[44:45], v[20:23], off offset:256
	s_and_saveexec_b64 s[44:45], s[0:1]
	s_cbranch_execz .LBB0_1013
	v_lshlrev_b64 v[20:21], 6, v[34:35]
	v_lshl_add_u64 v[20:21], s[16:17], 0, v[20:21]
	v_lshl_add_u64 v[20:21], s[6:7], 2, v[20:21]
	s_lshl_b32 s10, s70, 2
	v_lshl_add_u64 v[20:21], v[20:21], 0, s[10:11]
	s_waitcnt lgkmcnt(0)
	v_add_f32_e32 v18, v18, v19
	global_store_dword v[20:21], v18, off
.LBB0_1013:
	s_or_b64 exec, exec, s[44:45]
	v_add_u32_e32 v18, 0xb0, v204
	s_waitcnt lgkmcnt(0)
	v_ashrrev_i32_e32 v19, 31, v18
	v_lshlrev_b64 v[20:21], 10, v[18:19]
	v_lshl_add_u64 v[20:21], v[20:21], 0, v[202:203]
	v_lshlrev_b64 v[28:29], 1, v[20:21]
	v_lshl_add_u64 v[30:31], s[20:21], 0, v[28:29]
	global_load_dwordx4 v[20:23], v[30:31], off
	global_load_dwordx4 v[24:27], v[30:31], off offset:256
	v_pk_add_f32 v[16:17], v[16:17], v[80:81]
	v_pk_add_f32 v[14:15], v[14:15], v[78:79]
	v_pk_add_f32 v[12:13], v[12:13], v[76:77]
	v_pk_add_f32 v[10:11], v[10:11], v[74:75]
	v_pk_add_f32 v[8:9], v[8:9], v[96:97]
	v_pk_add_f32 v[6:7], v[6:7], v[94:95]
	v_pk_add_f32 v[4:5], v[4:5], v[92:93]
	v_pk_add_f32 v[2:3], v[2:3], v[90:91]
	v_lshl_add_u64 v[28:29], s[14:15], 0, v[28:29]
	s_waitcnt vmcnt(1)
	v_lshlrev_b32_e32 v32, 16, v20
	v_and_b32_e32 v33, 0xffff0000, v20
	v_lshlrev_b32_e32 v20, 16, v21
	v_and_b32_e32 v21, 0xffff0000, v21
	v_lshlrev_b32_e32 v34, 16, v22
	v_and_b32_e32 v35, 0xffff0000, v22
	v_lshlrev_b32_e32 v22, 16, v23
	v_and_b32_e32 v23, 0xffff0000, v23
	s_waitcnt vmcnt(0)
	v_lshlrev_b32_e32 v36, 16, v24
	v_and_b32_e32 v37, 0xffff0000, v24
	v_lshlrev_b32_e32 v24, 16, v25
	v_and_b32_e32 v25, 0xffff0000, v25
	v_lshlrev_b32_e32 v38, 16, v26
	v_and_b32_e32 v39, 0xffff0000, v26
	v_lshlrev_b32_e32 v26, 16, v27
	v_and_b32_e32 v27, 0xffff0000, v27
	v_pk_fma_f32 v[16:17], v[68:69], v[16:17], v[20:21]
	v_pk_fma_f32 v[14:15], v[66:67], v[14:15], v[32:33]
	v_pk_fma_f32 v[12:13], v[72:73], v[12:13], v[22:23]
	v_pk_fma_f32 v[10:11], v[70:71], v[10:11], v[34:35]
	v_pk_fma_f32 v[20:21], v[84:85], v[8:9], v[24:25]
	v_pk_fma_f32 v[22:23], v[82:83], v[6:7], v[36:37]
	v_pk_fma_f32 v[24:25], v[88:89], v[4:5], v[26:27]
	v_pk_fma_f32 v[26:27], v[86:87], v[2:3], v[38:39]
	v_mul_f32_e32 v40, v15, v15
	v_mul_f32_e32 v41, v17, v17
	v_mul_f32_e32 v42, v11, v11
	v_mul_f32_e32 v43, v13, v13
	v_cvt_pk_bf16_f32 v2, v14, v15
	v_cvt_pk_bf16_f32 v3, v16, v17
	v_cvt_pk_bf16_f32 v4, v10, v11
	v_cvt_pk_bf16_f32 v5, v12, v13
	v_pk_mul_f32 v[32:33], v[158:159], v[16:17]
	v_pk_mul_f32 v[34:35], v[160:161], v[14:15]
	v_pk_mul_f32 v[36:37], v[154:155], v[12:13]
	v_pk_mul_f32 v[38:39], v[156:157], v[10:11]
	v_mul_f32_e32 v11, v23, v23
	v_mul_f32_e32 v13, v21, v21
	v_mul_f32_e32 v15, v27, v27
	v_mul_f32_e32 v17, v25, v25
	v_cvt_pk_bf16_f32 v6, v22, v23
	v_cvt_pk_bf16_f32 v7, v20, v21
	v_cvt_pk_bf16_f32 v8, v26, v27
	v_cvt_pk_bf16_f32 v9, v24, v25
	v_fmac_f32_e32 v40, v14, v14
	v_fmac_f32_e32 v41, v16, v16
	v_fmac_f32_e32 v42, v10, v10
	v_fmac_f32_e32 v43, v12, v12
	global_store_dwordx4 v[30:31], v[2:5], off
	v_fmac_f32_e32 v11, v22, v22
	v_fmac_f32_e32 v13, v20, v20
	v_cvt_pk_bf16_f32 v2, v34, v35
	v_cvt_pk_bf16_f32 v3, v32, v33
	v_cvt_pk_bf16_f32 v4, v38, v39
	v_cvt_pk_bf16_f32 v5, v36, v37
	v_fmac_f32_e32 v15, v26, v26
	v_fmac_f32_e32 v17, v24, v24
	global_store_dwordx4 v[30:31], v[6:9], off offset:256
	global_store_dwordx4 v[28:29], v[2:5], off
	s_nop 0
	v_add_f32_e32 v6, v40, v41
	v_add_f32_e32 v7, v42, v43
	v_add_f32_e32 v2, v11, v13
	v_add_f32_e32 v3, v15, v17
	v_add_f32_e32 v4, v6, v7
	v_add_f32_e32 v2, v2, v3
	v_add_f32_e32 v5, v4, v2
	v_mov_b32_e32 v12, v5
	s_nop 1
	v_permlane16_swap_b32_e32 v5, v12
	v_pk_mul_f32 v[2:3], v[146:147], v[22:23]
	v_pk_mul_f32 v[6:7], v[152:153], v[20:21]
	v_cvt_pk_bf16_f32 v4, v2, v3
	v_pk_mul_f32 v[8:9], v[148:149], v[24:25]
	s_waitcnt lgkmcnt(0)
	v_add_f32_e32 v2, v5, v12
	v_mov_b32_e32 v3, v2
	s_nop 1
	v_permlane32_swap_b32_e32 v2, v3
	v_pk_mul_f32 v[10:11], v[150:151], v[26:27]
	v_cvt_pk_bf16_f32 v5, v6, v7
	v_cvt_pk_bf16_f32 v6, v10, v11
	v_cvt_pk_bf16_f32 v7, v8, v9
	global_store_dwordx4 v[28:29], v[4:7], off offset:256
	s_and_saveexec_b64 s[44:45], s[0:1]
	s_cbranch_execz .LBB0_1015
	v_lshlrev_b64 v[4:5], 6, v[18:19]
	v_lshl_add_u64 v[4:5], s[16:17], 0, v[4:5]
	v_lshl_add_u64 v[4:5], s[6:7], 2, v[4:5]
	s_lshl_b32 s10, s70, 2
	v_lshl_add_u64 v[4:5], v[4:5], 0, s[10:11]
	s_waitcnt lgkmcnt(0)
	v_add_f32_e32 v2, v2, v3
	global_store_dword v[4:5], v2, off

.LBB0_1171:
	s_ashr_i32 s23, s22, 4
	s_mul_hi_i32 s25, s23, 0x6000
	s_mulk_i32 s23, 0x6000
	s_add_u32 s26, s43, s23
	s_addc_u32 s27, s44, s25
	s_lshl_b32 s23, s22, 8
	v_lshl_or_b32 v162, s24, 8, v184
	v_add_u32_e32 v164, s23, v182
	v_ashrrev_i32_e32 v163, 31, v162
	v_ashrrev_i32_e32 v165, 31, v164
	v_lshl_add_u64 v[178:179], v[162:163], 1, s[20:21]
	v_lshlrev_b64 v[104:105], 11, v[164:165]
	v_lshl_add_u64 v[104:105], v[178:179], 0, v[104:105]
	global_load_dwordx4 v[166:169], v[104:105], off
	global_load_dwordx4 v[170:173], v[104:105], off offset:256
	v_lshl_add_u64 v[104:105], v[162:163], 2, s[26:27]
	global_load_dwordx4 v[124:127], v[104:105], off
	global_load_dwordx4 v[116:119], v[104:105], off offset:16
	global_load_dwordx4 v[108:111], v[104:105], off offset:512
	s_nop 0
	global_load_dwordx4 v[104:107], v[104:105], off offset:528
	v_and_b32_e32 v175, 64, v204
	v_xor_b32_e32 v174, 16, v204
	v_add_u32_e32 v218, 64, v175
	v_cmp_lt_i32_e32 vcc, v174, v218
	s_waitcnt vmcnt(0)
	v_and_b32_e32 v175, 0xffff0000, v166
	v_cndmask_b32_e32 v174, v204, v174, vcc
	v_lshlrev_b32_e32 v215, 2, v174
	v_lshlrev_b32_e32 v174, 16, v166
	v_lshlrev_b32_e32 v166, 16, v167
	v_and_b32_e32 v167, 0xffff0000, v167
	v_lshlrev_b32_e32 v176, 16, v168
	v_and_b32_e32 v177, 0xffff0000, v168
	v_lshlrev_b32_e32 v168, 16, v169
	v_and_b32_e32 v169, 0xffff0000, v169
	v_lshlrev_b32_e32 v180, 16, v170
	v_and_b32_e32 v181, 0xffff0000, v170
	v_lshlrev_b32_e32 v170, 16, v171
	v_and_b32_e32 v171, 0xffff0000, v171
	v_lshlrev_b32_e32 v216, 16, v172
	v_and_b32_e32 v217, 0xffff0000, v172
	v_lshlrev_b32_e32 v172, 16, v173
	v_and_b32_e32 v173, 0xffff0000, v173
	v_pk_fma_f32 v[142:143], v[142:143], v[126:127], v[166:167]
	v_pk_fma_f32 v[140:141], v[140:141], v[124:125], v[174:175]
	v_pk_fma_f32 v[138:139], v[138:139], v[118:119], v[168:169]
	v_pk_fma_f32 v[136:137], v[136:137], v[116:117], v[176:177]
	v_pk_fma_f32 v[134:135], v[134:135], v[110:111], v[170:171]
	v_pk_fma_f32 v[132:133], v[132:133], v[108:109], v[180:181]
	v_pk_fma_f32 v[130:131], v[130:131], v[106:107], v[172:173]
	v_pk_fma_f32 v[128:129], v[128:129], v[104:105], v[216:217]
	v_mul_f32_e32 v166, v141, v141
	v_mul_f32_e32 v167, v143, v143
	v_mul_f32_e32 v168, v137, v137
	v_mul_f32_e32 v169, v139, v139
	v_mul_f32_e32 v170, v133, v133
	v_mul_f32_e32 v171, v135, v135
	v_mul_f32_e32 v172, v129, v129
	v_mul_f32_e32 v173, v131, v131
	v_fmac_f32_e32 v166, v140, v140
	v_fmac_f32_e32 v167, v142, v142
	v_fmac_f32_e32 v168, v136, v136
	v_fmac_f32_e32 v169, v138, v138
	v_fmac_f32_e32 v170, v132, v132
	v_fmac_f32_e32 v171, v134, v134
	v_fmac_f32_e32 v172, v128, v128
	v_fmac_f32_e32 v173, v130, v130
	v_add_f32_e32 v166, v166, v167
	v_add_f32_e32 v167, v168, v169
	v_add_f32_e32 v168, v170, v171
	v_add_f32_e32 v169, v172, v173
	v_add_f32_e32 v166, v166, v167
	v_add_f32_e32 v167, v168, v169
	v_add_f32_e32 v166, v166, v167
	v_mov_b32_e32 v167, v166
	s_nop 1
	v_permlane16_swap_b32_e32 v166, v167
	v_xor_b32_e32 v168, 32, v204
	v_cmp_lt_i32_e32 vcc, v168, v218
	s_waitcnt lgkmcnt(0)
	v_add_f32_e32 v166, v166, v167
	v_cndmask_b32_e32 v168, v204, v168, vcc
	v_lshlrev_b32_e32 v216, 2, v168
	v_mov_b32_e32 v167, v166
	s_nop 1
	v_permlane32_swap_b32_e32 v166, v167
	s_and_saveexec_b64 s[26:27], s[0:1]
	s_cbranch_execz .LBB0_1173
	s_waitcnt lgkmcnt(0)
	v_add_f32_e32 v166, v166, v167
	ds_write_b32 v205, v166
.LBB0_1173:
	s_or_b64 exec, exec, s[26:27]
	v_add_u32_e32 v168, s23, v185
	v_ashrrev_i32_e32 v169, 31, v168
	s_waitcnt lgkmcnt(0)
	v_lshlrev_b64 v[166:167], 11, v[168:169]
	v_lshl_add_u64 v[166:167], v[178:179], 0, v[166:167]
	global_load_dwordx4 v[170:173], v[166:167], off
	global_load_dwordx4 v[174:177], v[166:167], off offset:256
	s_waitcnt vmcnt(1)
	v_lshlrev_b32_e32 v166, 16, v170
	v_and_b32_e32 v167, 0xffff0000, v170
	v_lshlrev_b32_e32 v170, 16, v171
	v_and_b32_e32 v171, 0xffff0000, v171
	v_lshlrev_b32_e32 v180, 16, v172
	v_and_b32_e32 v181, 0xffff0000, v172
	v_lshlrev_b32_e32 v172, 16, v173
	v_and_b32_e32 v173, 0xffff0000, v173
	s_waitcnt vmcnt(0)
	v_lshlrev_b32_e32 v218, 16, v174
	v_and_b32_e32 v219, 0xffff0000, v174
	v_lshlrev_b32_e32 v174, 16, v175
	v_and_b32_e32 v175, 0xffff0000, v175
	v_lshlrev_b32_e32 v220, 16, v176
	v_and_b32_e32 v221, 0xffff0000, v176
	v_lshlrev_b32_e32 v176, 16, v177
	v_and_b32_e32 v177, 0xffff0000, v177
	v_pk_fma_f32 v[122:123], v[122:123], v[126:127], v[170:171]
	v_pk_fma_f32 v[120:121], v[120:121], v[124:125], v[166:167]
	v_pk_fma_f32 v[114:115], v[114:115], v[118:119], v[172:173]
	v_pk_fma_f32 v[112:113], v[112:113], v[116:117], v[180:181]
	v_pk_fma_f32 v[102:103], v[102:103], v[110:111], v[174:175]
	v_pk_fma_f32 v[100:101], v[100:101], v[108:109], v[218:219]
	v_pk_fma_f32 v[98:99], v[98:99], v[106:107], v[176:177]
	v_pk_fma_f32 v[96:97], v[96:97], v[104:105], v[220:221]
	v_mul_f32_e32 v166, v121, v121
	v_mul_f32_e32 v167, v123, v123
	v_mul_f32_e32 v170, v113, v113
	v_mul_f32_e32 v171, v115, v115
	v_mul_f32_e32 v172, v101, v101
	v_mul_f32_e32 v173, v103, v103
	v_mul_f32_e32 v174, v97, v97
	v_mul_f32_e32 v175, v99, v99
	v_fmac_f32_e32 v166, v120, v120
	v_fmac_f32_e32 v167, v122, v122
	v_fmac_f32_e32 v170, v112, v112
	v_fmac_f32_e32 v171, v114, v114
	v_fmac_f32_e32 v172, v100, v100
	v_fmac_f32_e32 v173, v102, v102
	v_fmac_f32_e32 v174, v96, v96
	v_fmac_f32_e32 v175, v98, v98
	v_add_f32_e32 v166, v166, v167
	v_add_f32_e32 v167, v170, v171
	v_add_f32_e32 v170, v172, v173
	v_add_f32_e32 v171, v174, v175
	v_add_f32_e32 v166, v166, v167
	v_add_f32_e32 v167, v170, v171
	v_add_f32_e32 v166, v166, v167
	v_mov_b32_e32 v167, v166
	s_nop 1
	v_permlane16_swap_b32_e32 v166, v167
	s_nop 1
	s_waitcnt lgkmcnt(0)
	v_add_f32_e32 v166, v166, v167
	v_mov_b32_e32 v167, v166
	s_nop 1
	v_permlane32_swap_b32_e32 v166, v167
	s_and_saveexec_b64 s[26:27], s[0:1]
	s_cbranch_execz .LBB0_1175
	s_waitcnt lgkmcnt(0)
	v_add_f32_e32 v166, v166, v167
	ds_write_b32 v206, v166
.LBB0_1175:
	s_or_b64 exec, exec, s[26:27]
	v_add_u32_e32 v172, s23, v186
	v_ashrrev_i32_e32 v173, 31, v172
	s_waitcnt lgkmcnt(0)
	v_lshlrev_b64 v[166:167], 11, v[172:173]
	v_lshl_add_u64 v[166:167], v[178:179], 0, v[166:167]
	global_load_dwordx4 v[174:177], v[166:167], off
	global_load_dwordx4 v[218:221], v[166:167], off offset:256
	s_waitcnt vmcnt(1)
	v_lshlrev_b32_e32 v166, 16, v174
	v_and_b32_e32 v167, 0xffff0000, v174
	v_lshlrev_b32_e32 v170, 16, v175
	v_and_b32_e32 v171, 0xffff0000, v175
	v_lshlrev_b32_e32 v174, 16, v176
	v_and_b32_e32 v175, 0xffff0000, v176
	v_lshlrev_b32_e32 v176, 16, v177
	v_and_b32_e32 v177, 0xffff0000, v177
	s_waitcnt vmcnt(0)
	v_lshlrev_b32_e32 v180, 16, v218
	v_and_b32_e32 v181, 0xffff0000, v218
	v_lshlrev_b32_e32 v218, 16, v219
	v_and_b32_e32 v219, 0xffff0000, v219
	v_lshlrev_b32_e32 v222, 16, v220
	v_and_b32_e32 v223, 0xffff0000, v220
	v_lshlrev_b32_e32 v220, 16, v221
	v_and_b32_e32 v221, 0xffff0000, v221
	v_pk_fma_f32 v[94:95], v[94:95], v[126:127], v[170:171]
	v_pk_fma_f32 v[92:93], v[92:93], v[124:125], v[166:167]
	v_pk_fma_f32 v[90:91], v[90:91], v[118:119], v[176:177]
	v_pk_fma_f32 v[88:89], v[88:89], v[116:117], v[174:175]
	v_pk_fma_f32 v[86:87], v[86:87], v[110:111], v[218:219]
	v_pk_fma_f32 v[84:85], v[84:85], v[108:109], v[180:181]
	v_pk_fma_f32 v[82:83], v[82:83], v[106:107], v[220:221]
	v_pk_fma_f32 v[80:81], v[80:81], v[104:105], v[222:223]
	v_mul_f32_e32 v166, v93, v93
	v_mul_f32_e32 v167, v95, v95
	v_mul_f32_e32 v170, v89, v89
	v_mul_f32_e32 v171, v91, v91
	v_mul_f32_e32 v174, v85, v85
	v_mul_f32_e32 v175, v87, v87
	v_mul_f32_e32 v176, v81, v81
	v_mul_f32_e32 v177, v83, v83
	v_fmac_f32_e32 v166, v92, v92
	v_fmac_f32_e32 v167, v94, v94
	v_fmac_f32_e32 v170, v88, v88
	v_fmac_f32_e32 v171, v90, v90
	v_fmac_f32_e32 v174, v84, v84
	v_fmac_f32_e32 v175, v86, v86
	v_fmac_f32_e32 v176, v80, v80
	v_fmac_f32_e32 v177, v82, v82
	v_add_f32_e32 v166, v166, v167
	v_add_f32_e32 v167, v170, v171
	v_add_f32_e32 v170, v174, v175
	v_add_f32_e32 v171, v176, v177
	v_add_f32_e32 v166, v166, v167
	v_add_f32_e32 v167, v170, v171
	v_add_f32_e32 v166, v166, v167
	v_mov_b32_e32 v167, v166
	s_nop 1
	v_permlane16_swap_b32_e32 v166, v167
	s_nop 1
	s_waitcnt lgkmcnt(0)
	v_add_f32_e32 v166, v166, v167
	v_mov_b32_e32 v167, v166
	s_nop 1
	v_permlane32_swap_b32_e32 v166, v167
	s_and_saveexec_b64 s[26:27], s[0:1]
	s_cbranch_execz .LBB0_1177
	s_waitcnt lgkmcnt(0)
	v_add_f32_e32 v166, v166, v167
	ds_write_b32 v207, v166
.LBB0_1177:
	s_or_b64 exec, exec, s[26:27]
	v_add_u32_e32 v166, s23, v187
	s_waitcnt lgkmcnt(0)
	v_ashrrev_i32_e32 v167, 31, v166
	v_lshlrev_b64 v[170:171], 11, v[166:167]
	v_lshl_add_u64 v[170:171], v[178:179], 0, v[170:171]
	global_load_dwordx4 v[174:177], v[170:171], off
	global_load_dwordx4 v[218:221], v[170:171], off offset:256
	s_waitcnt vmcnt(1)
	v_lshlrev_b32_e32 v170, 16, v174
	v_and_b32_e32 v171, 0xffff0000, v174
	v_lshlrev_b32_e32 v174, 16, v175
	v_and_b32_e32 v175, 0xffff0000, v175
	v_lshlrev_b32_e32 v180, 16, v176
	v_and_b32_e32 v181, 0xffff0000, v176
	v_lshlrev_b32_e32 v176, 16, v177
	v_and_b32_e32 v177, 0xffff0000, v177
	s_waitcnt vmcnt(0)
	v_lshlrev_b32_e32 v222, 16, v218
	v_and_b32_e32 v223, 0xffff0000, v218
	v_lshlrev_b32_e32 v218, 16, v219
	v_and_b32_e32 v219, 0xffff0000, v219
	v_lshlrev_b32_e32 v224, 16, v220
	v_and_b32_e32 v225, 0xffff0000, v220
	v_lshlrev_b32_e32 v220, 16, v221
	v_and_b32_e32 v221, 0xffff0000, v221
	v_pk_fma_f32 v[78:79], v[78:79], v[126:127], v[174:175]
	v_pk_fma_f32 v[76:77], v[76:77], v[124:125], v[170:171]
	v_pk_fma_f32 v[74:75], v[74:75], v[118:119], v[176:177]
	v_pk_fma_f32 v[72:73], v[72:73], v[116:117], v[180:181]
	v_pk_fma_f32 v[70:71], v[70:71], v[110:111], v[218:219]
	v_pk_fma_f32 v[68:69], v[68:69], v[108:109], v[222:223]
	v_pk_fma_f32 v[66:67], v[66:67], v[106:107], v[220:221]
	v_pk_fma_f32 v[64:65], v[64:65], v[104:105], v[224:225]
	v_mul_f32_e32 v170, v77, v77
	v_mul_f32_e32 v171, v79, v79
	v_mul_f32_e32 v174, v73, v73
	v_mul_f32_e32 v175, v75, v75
	v_mul_f32_e32 v176, v69, v69
	v_mul_f32_e32 v177, v71, v71
	v_mul_f32_e32 v180, v65, v65
	v_mul_f32_e32 v181, v67, v67
	v_fmac_f32_e32 v170, v76, v76
	v_fmac_f32_e32 v171, v78, v78
	v_fmac_f32_e32 v174, v72, v72
	v_fmac_f32_e32 v175, v74, v74
	v_fmac_f32_e32 v176, v68, v68
	v_fmac_f32_e32 v177, v70, v70
	v_fmac_f32_e32 v180, v64, v64
	v_fmac_f32_e32 v181, v66, v66
	v_add_f32_e32 v170, v170, v171
	v_add_f32_e32 v171, v174, v175
	v_add_f32_e32 v174, v176, v177
	v_add_f32_e32 v175, v180, v181
	v_add_f32_e32 v170, v170, v171
	v_add_f32_e32 v171, v174, v175
	v_add_f32_e32 v170, v170, v171
	v_mov_b32_e32 v171, v170
	s_nop 1
	v_permlane16_swap_b32_e32 v170, v171
	s_nop 1
	s_waitcnt lgkmcnt(0)
	v_add_f32_e32 v170, v170, v171
	v_mov_b32_e32 v171, v170
	s_nop 1
	v_permlane32_swap_b32_e32 v170, v171
	s_and_saveexec_b64 s[26:27], s[0:1]
	s_cbranch_execz .LBB0_1179
	s_waitcnt lgkmcnt(0)
	v_add_f32_e32 v170, v170, v171
	ds_write_b32 v208, v170
.LBB0_1179:
	s_or_b64 exec, exec, s[26:27]
	v_add_u32_e32 v170, s23, v188
	s_waitcnt lgkmcnt(0)
	v_ashrrev_i32_e32 v171, 31, v170
	v_lshlrev_b64 v[174:175], 11, v[170:171]
	v_lshl_add_u64 v[180:181], v[178:179], 0, v[174:175]
	global_load_dwordx4 v[174:177], v[180:181], off
	global_load_dwordx4 v[218:221], v[180:181], off offset:256
	s_waitcnt vmcnt(1)
	v_lshlrev_b32_e32 v180, 16, v174
	v_and_b32_e32 v181, 0xffff0000, v174
	v_lshlrev_b32_e32 v174, 16, v175
	v_and_b32_e32 v175, 0xffff0000, v175
	v_lshlrev_b32_e32 v222, 16, v176
	v_and_b32_e32 v223, 0xffff0000, v176
	v_lshlrev_b32_e32 v176, 16, v177
	v_and_b32_e32 v177, 0xffff0000, v177
	s_waitcnt vmcnt(0)
	v_lshlrev_b32_e32 v224, 16, v218
	v_and_b32_e32 v225, 0xffff0000, v218
	v_lshlrev_b32_e32 v218, 16, v219
	v_and_b32_e32 v219, 0xffff0000, v219
	v_lshlrev_b32_e32 v226, 16, v220
	v_and_b32_e32 v227, 0xffff0000, v220
	v_lshlrev_b32_e32 v220, 16, v221
	v_and_b32_e32 v221, 0xffff0000, v221
	v_pk_fma_f32 v[62:63], v[62:63], v[126:127], v[174:175]
	v_pk_fma_f32 v[60:61], v[60:61], v[124:125], v[180:181]
	v_pk_fma_f32 v[58:59], v[58:59], v[118:119], v[176:177]
	v_pk_fma_f32 v[56:57], v[56:57], v[116:117], v[222:223]
	v_pk_fma_f32 v[54:55], v[54:55], v[110:111], v[218:219]
	v_pk_fma_f32 v[52:53], v[52:53], v[108:109], v[224:225]
	v_pk_fma_f32 v[50:51], v[50:51], v[106:107], v[220:221]
	v_pk_fma_f32 v[48:49], v[48:49], v[104:105], v[226:227]
	v_mul_f32_e32 v174, v61, v61
	v_mul_f32_e32 v175, v63, v63
	v_mul_f32_e32 v176, v57, v57
	v_mul_f32_e32 v177, v59, v59
	v_mul_f32_e32 v180, v53, v53
	v_mul_f32_e32 v181, v55, v55
	v_mul_f32_e32 v217, v49, v49
	v_mul_f32_e32 v218, v51, v51
	v_fmac_f32_e32 v174, v60, v60
	v_fmac_f32_e32 v175, v62, v62
	v_fmac_f32_e32 v176, v56, v56
	v_fmac_f32_e32 v177, v58, v58
	v_fmac_f32_e32 v180, v52, v52
	v_fmac_f32_e32 v181, v54, v54
	v_fmac_f32_e32 v217, v48, v48
	v_fmac_f32_e32 v218, v50, v50
	v_add_f32_e32 v174, v174, v175
	v_add_f32_e32 v175, v176, v177
	v_add_f32_e32 v176, v180, v181
	v_add_f32_e32 v177, v217, v218
	v_add_f32_e32 v174, v174, v175
	v_add_f32_e32 v175, v176, v177
	v_add_f32_e32 v174, v174, v175
	v_mov_b32_e32 v175, v174
	s_nop 1
	v_permlane16_swap_b32_e32 v174, v175
	s_nop 1
	s_waitcnt lgkmcnt(0)
	v_add_f32_e32 v174, v174, v175
	v_mov_b32_e32 v175, v174
	s_nop 1
	v_permlane32_swap_b32_e32 v174, v175
	s_and_saveexec_b64 s[26:27], s[0:1]
	s_cbranch_execz .LBB0_1181
	s_waitcnt lgkmcnt(0)
	v_add_f32_e32 v174, v174, v175
	ds_write_b32 v209, v174
.LBB0_1181:
	s_or_b64 exec, exec, s[26:27]
	v_add_u32_e32 v174, s23, v189
	s_waitcnt lgkmcnt(0)
	v_ashrrev_i32_e32 v175, 31, v174
	v_lshlrev_b64 v[176:177], 11, v[174:175]
	v_lshl_add_u64 v[176:177], v[178:179], 0, v[176:177]
	global_load_dwordx4 v[218:221], v[176:177], off
	global_load_dwordx4 v[222:225], v[176:177], off offset:256
	s_waitcnt vmcnt(1)
	v_lshlrev_b32_e32 v176, 16, v218
	v_and_b32_e32 v177, 0xffff0000, v218
	v_lshlrev_b32_e32 v180, 16, v219
	v_and_b32_e32 v181, 0xffff0000, v219
	v_lshlrev_b32_e32 v218, 16, v220
	v_and_b32_e32 v219, 0xffff0000, v220
	v_lshlrev_b32_e32 v220, 16, v221
	v_and_b32_e32 v221, 0xffff0000, v221
	s_waitcnt vmcnt(0)
	v_lshlrev_b32_e32 v226, 16, v222
	v_and_b32_e32 v227, 0xffff0000, v222
	v_lshlrev_b32_e32 v222, 16, v223
	v_and_b32_e32 v223, 0xffff0000, v223
	v_lshlrev_b32_e32 v228, 16, v224
	v_and_b32_e32 v229, 0xffff0000, v224
	v_lshlrev_b32_e32 v224, 16, v225
	v_and_b32_e32 v225, 0xffff0000, v225
	v_pk_fma_f32 v[46:47], v[46:47], v[126:127], v[180:181]
	v_pk_fma_f32 v[44:45], v[44:45], v[124:125], v[176:177]
	v_pk_fma_f32 v[42:43], v[42:43], v[118:119], v[220:221]
	v_pk_fma_f32 v[40:41], v[40:41], v[116:117], v[218:219]
	v_pk_fma_f32 v[38:39], v[38:39], v[110:111], v[222:223]
	v_pk_fma_f32 v[36:37], v[36:37], v[108:109], v[226:227]
	v_pk_fma_f32 v[34:35], v[34:35], v[106:107], v[224:225]
	v_pk_fma_f32 v[32:33], v[32:33], v[104:105], v[228:229]
	v_mul_f32_e32 v176, v45, v45
	v_mul_f32_e32 v177, v47, v47
	v_mul_f32_e32 v180, v41, v41
	v_mul_f32_e32 v181, v43, v43
	v_mul_f32_e32 v217, v37, v37
	v_mul_f32_e32 v218, v39, v39
	v_mul_f32_e32 v219, v33, v33
	v_mul_f32_e32 v220, v35, v35
	v_fmac_f32_e32 v176, v44, v44
	v_fmac_f32_e32 v177, v46, v46
	v_fmac_f32_e32 v180, v40, v40
	v_fmac_f32_e32 v181, v42, v42
	v_fmac_f32_e32 v217, v36, v36
	v_fmac_f32_e32 v218, v38, v38
	v_fmac_f32_e32 v219, v32, v32
	v_fmac_f32_e32 v220, v34, v34
	v_add_f32_e32 v176, v176, v177
	v_add_f32_e32 v177, v180, v181
	v_add_f32_e32 v180, v217, v218
	v_add_f32_e32 v181, v219, v220
	v_add_f32_e32 v176, v176, v177
	v_add_f32_e32 v177, v180, v181
	v_add_f32_e32 v176, v176, v177
	v_mov_b32_e32 v177, v176
	s_nop 1
	v_permlane16_swap_b32_e32 v176, v177
	s_nop 1
	s_waitcnt lgkmcnt(0)
	v_add_f32_e32 v176, v176, v177
	v_mov_b32_e32 v177, v176
	s_nop 1
	v_permlane32_swap_b32_e32 v176, v177
	s_and_saveexec_b64 s[26:27], s[0:1]
	s_cbranch_execz .LBB0_1183
	s_waitcnt lgkmcnt(0)
	v_add_f32_e32 v176, v176, v177
	ds_write_b32 v210, v176
.LBB0_1183:
	s_or_b64 exec, exec, s[26:27]
	v_add_u32_e32 v176, s23, v190
	s_waitcnt lgkmcnt(0)
	v_ashrrev_i32_e32 v177, 31, v176
	v_lshlrev_b64 v[180:181], 11, v[176:177]
	v_lshl_add_u64 v[180:181], v[178:179], 0, v[180:181]
	global_load_dwordx4 v[218:221], v[180:181], off
	global_load_dwordx4 v[222:225], v[180:181], off offset:256
	s_waitcnt vmcnt(1)
	v_lshlrev_b32_e32 v180, 16, v218
	v_and_b32_e32 v181, 0xffff0000, v218
	v_lshlrev_b32_e32 v218, 16, v219
	v_and_b32_e32 v219, 0xffff0000, v219
	v_lshlrev_b32_e32 v226, 16, v220
	v_and_b32_e32 v227, 0xffff0000, v220
	v_lshlrev_b32_e32 v220, 16, v221
	v_and_b32_e32 v221, 0xffff0000, v221
	s_waitcnt vmcnt(0)
	v_lshlrev_b32_e32 v228, 16, v222
	v_and_b32_e32 v229, 0xffff0000, v222
	v_lshlrev_b32_e32 v222, 16, v223
	v_and_b32_e32 v223, 0xffff0000, v223
	v_lshlrev_b32_e32 v230, 16, v224
	v_and_b32_e32 v231, 0xffff0000, v224
	v_lshlrev_b32_e32 v224, 16, v225
	v_and_b32_e32 v225, 0xffff0000, v225
	v_pk_fma_f32 v[30:31], v[30:31], v[126:127], v[218:219]
	v_pk_fma_f32 v[28:29], v[28:29], v[124:125], v[180:181]
	v_pk_fma_f32 v[26:27], v[26:27], v[118:119], v[220:221]
	v_pk_fma_f32 v[24:25], v[24:25], v[116:117], v[226:227]
	v_pk_fma_f32 v[22:23], v[22:23], v[110:111], v[222:223]
	v_pk_fma_f32 v[20:21], v[20:21], v[108:109], v[228:229]
	v_pk_fma_f32 v[18:19], v[18:19], v[106:107], v[224:225]
	v_pk_fma_f32 v[16:17], v[16:17], v[104:105], v[230:231]
	v_mul_f32_e32 v180, v29, v29
	v_mul_f32_e32 v181, v31, v31
	v_mul_f32_e32 v217, v25, v25
	v_mul_f32_e32 v218, v27, v27
	v_mul_f32_e32 v219, v21, v21
	v_mul_f32_e32 v220, v23, v23
	v_mul_f32_e32 v221, v17, v17
	v_mul_f32_e32 v222, v19, v19
	v_fmac_f32_e32 v180, v28, v28
	v_fmac_f32_e32 v181, v30, v30
	v_fmac_f32_e32 v217, v24, v24
	v_fmac_f32_e32 v218, v26, v26
	v_fmac_f32_e32 v219, v20, v20
	v_fmac_f32_e32 v220, v22, v22
	v_fmac_f32_e32 v221, v16, v16
	v_fmac_f32_e32 v222, v18, v18
	v_add_f32_e32 v180, v180, v181
	v_add_f32_e32 v181, v217, v218
	v_add_f32_e32 v217, v219, v220
	v_add_f32_e32 v218, v221, v222
	v_add_f32_e32 v180, v180, v181
	v_add_f32_e32 v181, v217, v218
	v_add_f32_e32 v180, v180, v181
	v_mov_b32_e32 v181, v180
	s_nop 1
	v_permlane16_swap_b32_e32 v180, v181
	s_nop 1
	s_waitcnt lgkmcnt(0)
	v_add_f32_e32 v180, v180, v181
	v_mov_b32_e32 v181, v180
	s_nop 1
	v_permlane32_swap_b32_e32 v180, v181
	s_and_saveexec_b64 s[26:27], s[0:1]
	s_cbranch_execz .LBB0_1185
	s_waitcnt lgkmcnt(0)
	v_add_f32_e32 v180, v180, v181
	ds_write_b32 v211, v180
.LBB0_1185:
	s_or_b64 exec, exec, s[26:27]
	v_add_u32_e32 v180, s23, v191
	s_waitcnt lgkmcnt(0)
	v_ashrrev_i32_e32 v181, 31, v180
	v_lshlrev_b64 v[218:219], 11, v[180:181]
	v_lshl_add_u64 v[178:179], v[178:179], 0, v[218:219]
	global_load_dwordx4 v[218:221], v[178:179], off
	global_load_dwordx4 v[222:225], v[178:179], off offset:256
	s_waitcnt vmcnt(1)
	v_lshlrev_b32_e32 v178, 16, v218
	v_and_b32_e32 v179, 0xffff0000, v218
	v_lshlrev_b32_e32 v218, 16, v219
	v_and_b32_e32 v219, 0xffff0000, v219
	v_lshlrev_b32_e32 v226, 16, v220
	v_and_b32_e32 v227, 0xffff0000, v220
	v_lshlrev_b32_e32 v220, 16, v221
	v_and_b32_e32 v221, 0xffff0000, v221
	s_waitcnt vmcnt(0)
	v_lshlrev_b32_e32 v228, 16, v222
	v_and_b32_e32 v229, 0xffff0000, v222
	v_lshlrev_b32_e32 v222, 16, v223
	v_and_b32_e32 v223, 0xffff0000, v223
	v_lshlrev_b32_e32 v230, 16, v224
	v_and_b32_e32 v231, 0xffff0000, v224
	v_lshlrev_b32_e32 v224, 16, v225
	v_and_b32_e32 v225, 0xffff0000, v225
	v_pk_fma_f32 v[126:127], v[14:15], v[126:127], v[218:219]
	v_pk_fma_f32 v[124:125], v[12:13], v[124:125], v[178:179]
	v_pk_fma_f32 v[118:119], v[10:11], v[118:119], v[220:221]
	v_pk_fma_f32 v[116:117], v[8:9], v[116:117], v[226:227]
	v_pk_fma_f32 v[110:111], v[6:7], v[110:111], v[222:223]
	v_pk_fma_f32 v[108:109], v[4:5], v[108:109], v[228:229]
	v_pk_fma_f32 v[106:107], v[2:3], v[106:107], v[224:225]
	v_pk_fma_f32 v[104:105], v[0:1], v[104:105], v[230:231]
	v_mul_f32_e32 v0, v125, v125
	v_mul_f32_e32 v1, v127, v127
	v_mul_f32_e32 v2, v117, v117
	v_mul_f32_e32 v3, v119, v119
	v_mul_f32_e32 v4, v109, v109
	v_mul_f32_e32 v5, v111, v111
	v_mul_f32_e32 v6, v105, v105
	v_mul_f32_e32 v7, v107, v107
	v_fmac_f32_e32 v0, v124, v124
	v_fmac_f32_e32 v1, v126, v126
	v_fmac_f32_e32 v2, v116, v116
	v_fmac_f32_e32 v3, v118, v118
	v_fmac_f32_e32 v4, v108, v108
	v_fmac_f32_e32 v5, v110, v110
	v_fmac_f32_e32 v6, v104, v104
	v_fmac_f32_e32 v7, v106, v106
	v_add_f32_e32 v0, v0, v1
	v_add_f32_e32 v1, v2, v3
	v_add_f32_e32 v2, v4, v5
	v_add_f32_e32 v3, v6, v7
	v_add_f32_e32 v0, v0, v1
	v_add_f32_e32 v1, v2, v3
	v_add_f32_e32 v0, v0, v1
	v_mov_b32_e32 v1, v0
	s_nop 1
	v_permlane16_swap_b32_e32 v0, v1
	s_nop 1
	s_waitcnt lgkmcnt(0)
	v_add_f32_e32 v0, v0, v1
	v_mov_b32_e32 v1, v0
	s_nop 1
	v_permlane32_swap_b32_e32 v0, v1
	s_and_saveexec_b64 s[26:27], s[0:1]
	s_cbranch_execz .LBB0_1187
	s_waitcnt lgkmcnt(0)
	v_add_f32_e32 v0, v0, v1
	ds_write_b32 v212, v0
